# nt hint on more read-once streams: P0 w_in transposes, P2 raw unit rows, P3 HGRN2 scan operands, P3 weight-copy sources
# speedup vs baseline: 1.0149x; 1.0149x over previous
; __host__ __device__ __forceinline__ int tile_slot(int pn) { if (pn >= 16) return pn - 12; const int q = pn & 7; if (q >= 6) return (pn >> 3) * 2 + (q - 6); return (pn >> 3) * 6 + q; }
; #define GAS __attribute__((address_space(1)))
; #define LAS __attribute__((address_space(3)))
; #define LDS_WAIT() asm volatile("s_waitcnt lgkmcnt(0)" ::: "memory")
; __device__ __forceinline__ unsigned pk2(float lo, float hi) { const f32x2_t v = {lo, hi}; return __builtin_bit_cast(unsigned, __builtin_convertvector(v, bf16x2_t)); }
; __device__ __forceinline__ void p0_transpose_item(const float* W, int ldw, int src_col0, int k0, bf16_t* WT, int ldk, int dst_row0, int dst_k0, LAS float* scr, int lane) {
; #pragma unroll
;     for (int i = 0; i < 8; ++i) { const int kk = 8 * i + (lane >> 3), n4 = 4 * (lane & 7);
;         const f32x4 w = *(const GAS f32x4*)(W + (size_t)(k0 + kk) * ldw + src_col0 + n4); LAS float* d = scr + kk * 33 + n4; d[0] = w[0]; d[1] = w[1]; d[2] = w[2]; d[3] = w[3]; }
;     LDS_WAIT(); asm volatile("" ::: "memory");
;     const int c = lane & 7;
; #pragma unroll
;     for (int j = 0; j < 4; ++j) { const int n = (lane >> 3) + 8 * j; const LAS float* s = scr + (8 * c) * 33 + n;
;         v4u o; o.x = pk2(s[0 * 33], s[1 * 33]); o.y = pk2(s[2 * 33], s[3 * 33]); o.z = pk2(s[4 * 33], s[5 * 33]); o.w = pk2(s[6 * 33], s[7 * 33]);
;         *(GAS v4u*)(WT + (size_t)(dst_row0 + n) * ldk + dst_k0 + k0 + 8 * c) = o; }
;     LDS_WAIT(); asm volatile("" ::: "memory");
; }
; __global__ void __launch_bounds__(NWAVES * 64, 2) fwd(Args args) {
;     ...
;         for (int it = gw; it < I_IN; it += NGW) { const int kb = it / 192, nb = it % 192, pn = nb >> 3, row = tile_slot(pn) * 256 + (nb & 7) * 32;
;             p0_transpose_item(w_in, PROJW, orig_col(32 * nb), 64 * kb, tile_is_late(pn) ? WING_T : WIN_T, 1024, row, 0, scr, lane); }
.LBB0_20:
	s_lshl_b32 s8, s35, 8
	s_and_b32 s9, s36, 0xe0
	s_or_b32 s35, s8, s9
	s_lshl_b32 s8, s11, 6
	s_and_b32 s9, s33, 48
	s_cmp_eq_u32 s9, 48
	s_cselect_b64 s[36:37], -1, 0
	s_or_b64 s[6:7], s[6:7], s[36:37]
	s_and_b64 s[6:7], s[6:7], exec
	s_cselect_b32 s33, s5, s65
	s_cselect_b32 s36, s84, s64
	s_ashr_i32 s11, s10, 31
	v_lshl_add_u64 v[60:61], s[10:11], 2, v[4:5]
	v_or_b32_e32 v35, s8, v6
	v_mad_i64_i32 v[40:41], s[6:7], v35, s14, v[60:61]
	v_or_b32_e32 v35, s8, v7
	v_mad_i64_i32 v[44:45], s[6:7], v35, s14, v[60:61]
	v_or_b32_e32 v35, s8, v10
	v_or_b32_e32 v30, s8, v8
	v_or_b32_e32 v32, s8, v1
	v_mad_i64_i32 v[48:49], s[6:7], v35, s14, v[60:61]
	v_or_b32_e32 v35, s8, v11
	v_mad_i64_i32 v[30:31], s[6:7], v30, s14, v[60:61]
	v_mad_i64_i32 v[36:37], s[6:7], v32, s14, v[60:61]
	v_mad_i64_i32 v[52:53], s[6:7], v35, s14, v[60:61]
	global_load_dwordx4 v[30:33], v[30:31], off nt
	s_nop 0
	global_load_dwordx4 v[36:39], v[36:37], off nt
	s_nop 0
	global_load_dwordx4 v[40:43], v[40:41], off nt
	s_nop 0
	global_load_dwordx4 v[44:47], v[44:45], off nt
	s_nop 0
	global_load_dwordx4 v[48:51], v[48:49], off nt
	s_nop 0
	global_load_dwordx4 v[52:55], v[52:53], off nt
	v_or_b32_e32 v35, s8, v12
	v_mad_i64_i32 v[56:57], s[6:7], v35, s14, v[60:61]
	global_load_dwordx4 v[56:59], v[56:57], off nt
	v_or_b32_e32 v35, s8, v13
	v_mad_i64_i32 v[60:61], s[6:7], v35, s14, v[60:61]
	global_load_dwordx4 v[60:63], v[60:61], off nt
	s_ashr_i32 s9, s8, 31
	s_lshl_b64 s[6:7], s[8:9], 1
	v_or_b32_e32 v64, s35, v8
	s_add_u32 s6, s36, s6
	v_ashrrev_i32_e32 v65, 31, v64
	s_addc_u32 s7, s33, s7
	v_lshlrev_b64 v[64:65], 11, v[64:65]
	v_lshl_add_u64 v[68:69], s[6:7], 0, v[2:3]
	v_or_b32_e32 v66, s35, v1
	v_lshl_add_u64 v[64:65], v[68:69], 0, v[64:65]
	v_ashrrev_i32_e32 v67, 31, v66
	v_lshlrev_b64 v[66:67], 11, v[66:67]
	v_lshl_add_u64 v[66:67], v[68:69], 0, v[66:67]
	s_add_i32 s15, s15, s42
	s_add_i32 s3, s3, s4
	s_add_i32 s12, s12, s13
	s_cmpk_gt_i32 s15, 0xbff
	s_waitcnt vmcnt(7)
	ds_write2_b32 v15, v30, v31 offset1:1
	ds_write2_b32 v15, v32, v33 offset0:2 offset1:3
	s_waitcnt vmcnt(6)
	ds_write2_b32 v16, v36, v37 offset1:1
	ds_write2_b32 v17, v38, v39 offset1:1
	s_waitcnt vmcnt(5)
	ds_write2_b32 v18, v40, v41 offset1:1
	ds_write2_b32 v19, v42, v43 offset1:1
	s_waitcnt vmcnt(4)
	ds_write2_b32 v20, v44, v45 offset1:1
	ds_write2_b32 v21, v46, v47 offset1:1
	s_waitcnt vmcnt(3)
	ds_write2_b32 v22, v48, v49 offset1:1
	ds_write2_b32 v23, v50, v51 offset1:1
	s_waitcnt vmcnt(2)
	ds_write2_b32 v24, v52, v53 offset1:1
	ds_write2_b32 v25, v54, v55 offset1:1
	s_waitcnt vmcnt(1)
	ds_write2_b32 v26, v56, v57 offset1:1
	ds_write2_b32 v27, v58, v59 offset1:1
	s_waitcnt vmcnt(0)
	ds_write2_b32 v28, v60, v61 offset1:1
	ds_write2_b32 v29, v62, v63 offset1:1
	s_waitcnt lgkmcnt(0)
	ds_read2_b32 v[32:33], v14 offset0:33 offset1:41
	ds_read2_b32 v[36:37], v14 offset1:8
	ds_read2_b32 v[38:39], v14 offset0:66 offset1:74
	ds_read2_b32 v[40:41], v14 offset0:99 offset1:107
	ds_read2_b32 v[42:43], v14 offset0:132 offset1:140
	ds_read2_b32 v[44:45], v14 offset0:165 offset1:173
	ds_read2_b32 v[46:47], v14 offset0:198 offset1:206
	ds_read2_b32 v[48:49], v14 offset0:231 offset1:239
	ds_read2_b32 v[50:51], v14 offset0:49 offset1:57
	ds_read2_b32 v[52:53], v14 offset0:16 offset1:24
	ds_read2_b32 v[54:55], v14 offset0:82 offset1:90
	ds_read2_b32 v[56:57], v14 offset0:115 offset1:123
	ds_read2_b32 v[58:59], v14 offset0:148 offset1:156
	ds_read2_b32 v[60:61], v14 offset0:181 offset1:189
	s_waitcnt lgkmcnt(12)
	v_cvt_pk_bf16_f32 v30, v36, v32
	s_waitcnt lgkmcnt(10)
	v_cvt_pk_bf16_f32 v31, v38, v40
	v_cvt_pk_bf16_f32 v36, v37, v33
	s_waitcnt lgkmcnt(8)
	v_cvt_pk_bf16_f32 v32, v42, v44
	s_waitcnt lgkmcnt(6)
	v_cvt_pk_bf16_f32 v33, v46, v48
	global_store_dwordx4 v[64:65], v[30:33], off
	v_cvt_pk_bf16_f32 v37, v39, v41
	v_cvt_pk_bf16_f32 v38, v43, v45
	ds_read2_b32 v[40:41], v14 offset0:214 offset1:222
	ds_read2_b32 v[42:43], v14 offset0:247 offset1:255
	v_cvt_pk_bf16_f32 v39, v47, v49
	global_store_dwordx4 v[66:67], v[36:39], off
	s_waitcnt lgkmcnt(6)
	v_cvt_pk_bf16_f32 v30, v52, v50
	s_waitcnt lgkmcnt(4)
	v_cvt_pk_bf16_f32 v31, v54, v56
	v_or_b32_e32 v36, s35, v6
	v_ashrrev_i32_e32 v37, 31, v36
	v_lshlrev_b64 v[36:37], 11, v[36:37]
	s_waitcnt lgkmcnt(2)
	v_cvt_pk_bf16_f32 v32, v58, v60
	s_waitcnt lgkmcnt(0)
	v_cvt_pk_bf16_f32 v33, v40, v42
	v_lshl_add_u64 v[36:37], v[68:69], 0, v[36:37]
	global_store_dwordx4 v[36:37], v[30:33], off
	v_or_b32_e32 v36, s35, v7
	v_ashrrev_i32_e32 v37, 31, v36
	v_lshlrev_b64 v[36:37], 11, v[36:37]
	v_cvt_pk_bf16_f32 v30, v53, v51
	v_cvt_pk_bf16_f32 v31, v55, v57
	v_cvt_pk_bf16_f32 v32, v59, v61
	v_cvt_pk_bf16_f32 v33, v41, v43
	v_lshl_add_u64 v[36:37], v[68:69], 0, v[36:37]
	global_store_dwordx4 v[36:37], v[30:33], off
	s_waitcnt lgkmcnt(0)
	s_cbranch_scc1 .LBB0_43

; #define GAS __attribute__((address_space(1)))
; #define LAS __attribute__((address_space(3)))
; __device__ __forceinline__ void dn_load_raw(DnRaw& R, int unit, const bf16_t* DNR, const bf16_t* HALO, const float* GBT, int tid) {
;     const bf16_t* region = DNR + (size_t)unit * 32768; const int rb = unit >> 2, h = unit & 3, n = rb & (NCH - 1), cg = tid & 15, t0 = 2 * (tid >> 4);
; #pragma unroll
;     for (int part = 0; part < 3; ++part)
; #pragma unroll
;         for (int j = 0; j < 5; ++j) { const int t = t0 - 3 + j; v4u w4 = (v4u){0u, 0u, 0u, 0u};
;             if (t >= 0) w4 = *(const GAS v4u*)(region + part * 8192 + t * 128 + 8 * cg);
;             else if (n != 0) w4 = *(const GAS v4u*)(HALO + (size_t)(rb - 1) * 4608 + (t + 3) * 1536 + h * 384 + part * 128 + 8 * cg);
; __global__ void __launch_bounds__(NWAVES * 64, 2) fwd(Args args) {
;     ...
;             { const int h_ = (int)blockIdx.x & 3; LAS float* cw = (LAS float*)(lds + CONVW_OFF);
;               for (int i = tid; i < 1536; i += NWAVES * 64) { const int part = i >> 9, j = (i >> 7) & 3, cc = i & 127; cw[i] = args.in[3][j * 1536 + part * 512 + h_ * 128 + cc]; } }
.LBB0_319:
	v_add_u32_e32 v2, s3, v1
	v_lshl_add_u64 v[6:7], v[2:3], 2, s[22:23]
	global_load_dword v2, v[6:7], off nt
	s_addk_i32 s3, 0x200
	v_add_u32_e32 v5, s3, v0
	v_add_u32_e32 v5, 0xfffffe00, v5
	v_cmp_lt_u32_e32 vcc, s4, v5
	s_or_b64 s[6:7], vcc, s[6:7]
	s_waitcnt vmcnt(0)
	ds_write_b32 v4, v2
	v_add_u32_e32 v4, 0x800, v4
	s_andn2_b64 exec, exec, s[6:7]
	s_cbranch_execnz .LBB0_319
	s_or_b64 exec, exec, s[6:7]
	s_ashr_i32 s3, s2, 31
	s_lshl_b64 s[14:15], s[2:3], 16
	s_add_u32 s12, s62, s14
	s_addc_u32 s13, s63, s15
	s_ashr_i32 s33, s2, 2
	s_and_b32 s4, s2, 3
	s_and_b32 s6, s2, 0x1fc
	s_cmp_lg_u32 s6, 0
	s_cselect_b64 s[10:11], -1, 0
	s_add_i32 s6, s33, -1
	s_mul_hi_i32 s7, s6, 0x2400
	s_mulk_i32 s6, 0x2400
	s_add_u32 s6, s28, s6
	v_lshrrev_b32_e32 v1, 3, v0
	s_addc_u32 s7, s29, s7
	s_mul_i32 s8, s4, 0x300
	v_and_b32_e32 v44, 62, v1
	s_add_u32 s6, s6, s8
	s_addc_u32 s7, s7, 0
	v_lshlrev_b32_e32 v2, 3, v0
	v_cmp_gt_u32_e64 s[8:9], 3, v44
	s_mov_b64 s[16:17], 0
	s_and_saveexec_b64 s[22:23], s[8:9]
	s_xor_b64 s[22:23], exec, s[22:23]
	s_cbranch_execz .LBB0_325
	s_and_b64 vcc, exec, s[10:11]
	s_cbranch_vccz .LBB0_323
	v_mul_u32_u24_e32 v6, 0x600, v44
	s_mov_b64 s[16:17], -1
	s_branch .LBB0_324

; #define GAS __attribute__((address_space(1)))
; __device__ __forceinline__ void dn_load_raw(DnRaw& R, int unit, const bf16_t* DNR, const bf16_t* HALO, const float* GBT, int tid) {
;     ...
;         for (int j = 0; j < 5; ++j) { const int t = t0 - 3 + j; v4u w4 = (v4u){0u, 0u, 0u, 0u};
;             if (t >= 0) w4 = *(const GAS v4u*)(region + part * 8192 + t * 128 + 8 * cg);
;             else if (n != 0) w4 = *(const GAS v4u*)(HALO + (size_t)(rb - 1) * 4608 + (t + 3) * 1536 + h * 384 + part * 128 + 8 * cg);
;             R.w[part][j] = w4; }
.LBB0_325:
	s_or_saveexec_b64 s[22:23], s[22:23]
	v_add_u32_e32 v22, -3, v44
	v_and_b32_e32 v7, 0x78, v2
	v_mov_b64_e32 v[8:9], s[6:7]
	v_lshlrev_b32_e32 v46, 7, v22
	s_xor_b64 exec, exec, s[22:23]
	v_lshlrev_b32_e32 v6, 7, v22
	v_mov_b64_e32 v[8:9], s[12:13]
	s_or_b64 s[16:17], s[16:17], exec
	s_or_b64 exec, exec, s[22:23]
	v_mov_b32_e32 v113, 0
	v_mov_b32_e32 v2, v113
	v_mov_b32_e32 v3, v113
	v_mov_b32_e32 v4, v113
	v_mov_b32_e32 v5, v113
	v_lshlrev_b32_e32 v112, 1, v7
	s_and_saveexec_b64 s[22:23], s[16:17]
	s_cbranch_execz .LBB0_329
	v_lshl_add_u64 v[2:3], v[8:9], 0, v[112:113]
	v_mov_b32_e32 v7, v113
	v_lshl_add_u64 v[2:3], v[6:7], 1, v[2:3]
	global_load_dwordx4 v[2:5], v[2:3], off nt

; #define GAS __attribute__((address_space(1)))
; __device__ __forceinline__ void dn_load_raw(DnRaw& R, int unit, const bf16_t* DNR, const bf16_t* HALO, const float* GBT, int tid) {
;     ...
;         for (int j = 0; j < 5; ++j) { const int t = t0 - 3 + j; v4u w4 = (v4u){0u, 0u, 0u, 0u};
;             if (t >= 0) w4 = *(const GAS v4u*)(region + part * 8192 + t * 128 + 8 * cg);
;             else if (n != 0) w4 = *(const GAS v4u*)(HALO + (size_t)(rb - 1) * 4608 + (t + 3) * 1536 + h * 384 + part * 128 + 8 * cg);
;             R.w[part][j] = w4; }
.LBB0_334:
	s_or_saveexec_b64 s[22:23], s[22:23]
	v_add_u32_e32 v33, -2, v44
	v_lshl_add_u64 v[42:43], s[12:13], 0, v[112:113]
	v_lshlrev_b32_e32 v52, 7, v33
	s_xor_b64 exec, exec, s[22:23]
	v_lshlrev_b32_e32 v6, 7, v33
	v_mov_b32_e32 v7, 0
	v_lshl_add_u64 v[10:11], v[6:7], 1, v[42:43]
	s_or_b64 s[16:17], s[16:17], exec
	s_or_b64 exec, exec, s[22:23]
	v_mov_b32_e32 v6, 0
	v_mov_b32_e32 v7, v6
	v_mov_b32_e32 v8, v6
	v_mov_b32_e32 v9, v6
	s_and_saveexec_b64 s[12:13], s[16:17]
	s_cbranch_execz .LBB0_338
	global_load_dwordx4 v[6:9], v[10:11], off nt

; #define GAS __attribute__((address_space(1)))
; __device__ __forceinline__ void dn_load_raw(DnRaw& R, int unit, const bf16_t* DNR, const bf16_t* HALO, const float* GBT, int tid) {
;     ...
;         for (int j = 0; j < 5; ++j) { const int t = t0 - 3 + j; v4u w4 = (v4u){0u, 0u, 0u, 0u};
;             if (t >= 0) w4 = *(const GAS v4u*)(region + part * 8192 + t * 128 + 8 * cg);
;             else if (n != 0) w4 = *(const GAS v4u*)(HALO + (size_t)(rb - 1) * 4608 + (t + 3) * 1536 + h * 384 + part * 128 + 8 * cg);
;             R.w[part][j] = w4; }
.LBB0_343:
	s_or_saveexec_b64 s[16:17], s[16:17]
	v_add_u32_e32 v10, -1, v44
	v_lshlrev_b32_e32 v54, 7, v10
	s_xor_b64 exec, exec, s[16:17]
	v_mov_b32_e32 v55, 0
	v_lshl_add_u64 v[18:19], v[54:55], 1, v[42:43]
	s_or_b64 s[12:13], s[12:13], exec
	s_or_b64 exec, exec, s[16:17]
	v_mov_b32_e32 v14, 0
	v_mov_b32_e32 v15, v14
	v_mov_b32_e32 v16, v14
	v_mov_b32_e32 v17, v14
	v_mov_b64_e32 v[10:11], v[14:15]
	v_mov_b64_e32 v[12:13], v[16:17]
	s_and_saveexec_b64 s[16:17], s[12:13]
	s_cbranch_execz .LBB0_347
	global_load_dwordx4 v[10:13], v[18:19], off nt
.LBB0_347:
	s_or_b64 exec, exec, s[16:17]
	v_or_b32_e32 v53, 1, v1
	v_lshlrev_b32_e32 v16, 8, v44
	v_mov_b32_e32 v17, v14
	v_lshlrev_b32_e32 v18, 8, v53
	v_mov_b32_e32 v19, v14
	v_lshl_add_u64 v[16:17], v[42:43], 0, v[16:17]
	v_lshl_add_u64 v[18:19], v[42:43], 0, v[18:19]
	global_load_dwordx4 v[14:17], v[16:17], off nt
	s_nop 0
	global_load_dwordx4 v[18:21], v[18:19], off nt
	s_mov_b64 s[16:17], 0x100
	s_mov_b64 s[22:23], 0x4000
	s_mov_b64 s[12:13], 0
	s_and_saveexec_b64 s[36:37], s[8:9]
	s_xor_b64 s[36:37], exec, s[36:37]
	s_cbranch_execz .LBB0_352
	s_and_b64 vcc, exec, s[10:11]
	s_cbranch_vccz .LBB0_350
	v_mul_u32_u24_e32 v26, 0x600, v44
	s_mov_b64 s[12:13], -1
	s_branch .LBB0_351

; #define GAS __attribute__((address_space(1)))
; __device__ __forceinline__ void dn_load_raw(DnRaw& R, int unit, const bf16_t* DNR, const bf16_t* HALO, const float* GBT, int tid) {
;     ...
;         for (int j = 0; j < 5; ++j) { const int t = t0 - 3 + j; v4u w4 = (v4u){0u, 0u, 0u, 0u};
;             if (t >= 0) w4 = *(const GAS v4u*)(region + part * 8192 + t * 128 + 8 * cg);
;             else if (n != 0) w4 = *(const GAS v4u*)(HALO + (size_t)(rb - 1) * 4608 + (t + 3) * 1536 + h * 384 + part * 128 + 8 * cg);
;             R.w[part][j] = w4; }
.LBB0_352:
	s_or_saveexec_b64 s[36:37], s[36:37]
	v_lshl_add_u64 v[30:31], v[50:51], 0, s[16:17]
	v_lshl_add_u64 v[38:39], v[42:43], 0, s[22:23]
	v_mov_b64_e32 v[28:29], v[30:31]
	s_xor_b64 exec, exec, s[36:37]
	v_lshlrev_b32_e32 v26, 7, v22
	s_or_b64 s[12:13], s[12:13], exec
	v_mov_b64_e32 v[28:29], v[38:39]
	s_or_b64 exec, exec, s[36:37]
	v_mov_b32_e32 v22, 0
	v_mov_b32_e32 v23, v22
	v_mov_b32_e32 v24, v22
	v_mov_b32_e32 v25, v22
	s_and_saveexec_b64 s[16:17], s[12:13]
	s_cbranch_execz .LBB0_356
	v_mov_b32_e32 v27, v22
	v_lshl_add_u64 v[22:23], v[26:27], 1, v[28:29]
	global_load_dwordx4 v[22:25], v[22:23], off nt

; #define GAS __attribute__((address_space(1)))
; __device__ __forceinline__ void dn_load_raw(DnRaw& R, int unit, const bf16_t* DNR, const bf16_t* HALO, const float* GBT, int tid) {
;     ...
;         for (int j = 0; j < 5; ++j) { const int t = t0 - 3 + j; v4u w4 = (v4u){0u, 0u, 0u, 0u};
;             if (t >= 0) w4 = *(const GAS v4u*)(region + part * 8192 + t * 128 + 8 * cg);
;             else if (n != 0) w4 = *(const GAS v4u*)(HALO + (size_t)(rb - 1) * 4608 + (t + 3) * 1536 + h * 384 + part * 128 + 8 * cg);
;             R.w[part][j] = w4; }
.LBB0_361:
	s_andn2_saveexec_b64 s[16:17], s[16:17]
	v_lshlrev_b32_e32 v32, 7, v33
	s_or_b64 s[12:13], s[12:13], exec
	v_mov_b64_e32 v[30:31], v[38:39]
	s_or_b64 exec, exec, s[16:17]
	v_mov_b32_e32 v26, 0
	v_mov_b32_e32 v27, v26
	v_mov_b32_e32 v28, v26
	v_mov_b32_e32 v29, v26
	s_and_saveexec_b64 s[16:17], s[12:13]
	s_cbranch_execz .LBB0_365
	v_mov_b32_e32 v33, v26
	v_lshl_add_u64 v[26:27], v[32:33], 1, v[30:31]
	global_load_dwordx4 v[26:29], v[26:27], off nt

; #define GAS __attribute__((address_space(1)))
; __device__ __forceinline__ void dn_load_raw(DnRaw& R, int unit, const bf16_t* DNR, const bf16_t* HALO, const float* GBT, int tid) {
;     ...
;         for (int j = 0; j < 5; ++j) { const int t = t0 - 3 + j; v4u w4 = (v4u){0u, 0u, 0u, 0u};
;             if (t >= 0) w4 = *(const GAS v4u*)(region + part * 8192 + t * 128 + 8 * cg);
;             else if (n != 0) w4 = *(const GAS v4u*)(HALO + (size_t)(rb - 1) * 4608 + (t + 3) * 1536 + h * 384 + part * 128 + 8 * cg);
;             R.w[part][j] = w4; }
.LBB0_370:
	s_or_saveexec_b64 s[16:17], s[16:17]
	v_lshlrev_b32_e32 v45, 7, v44
	v_lshlrev_b32_e32 v47, 7, v53
	s_xor_b64 exec, exec, s[16:17]
	v_mov_b32_e32 v55, 0
	v_lshl_add_u64 v[40:41], v[54:55], 1, v[38:39]
	s_or_b64 s[12:13], s[12:13], exec
	s_or_b64 exec, exec, s[16:17]
	v_mov_b32_e32 v34, 0
	v_mov_b32_e32 v35, v34
	v_mov_b32_e32 v36, v34
	v_mov_b32_e32 v37, v34
	v_mov_b64_e32 v[30:31], v[34:35]
	v_mov_b64_e32 v[32:33], v[36:37]
	s_and_saveexec_b64 s[16:17], s[12:13]
	s_cbranch_execz .LBB0_374
	global_load_dwordx4 v[30:33], v[40:41], off nt
.LBB0_374:
	s_or_b64 exec, exec, s[16:17]
	v_lshlrev_b32_e32 v56, 1, v45
	v_mov_b32_e32 v57, v34
	v_lshlrev_b32_e32 v58, 1, v47
	v_mov_b32_e32 v59, v34
	v_lshl_add_u64 v[36:37], v[38:39], 0, v[56:57]
	v_lshl_add_u64 v[38:39], v[38:39], 0, v[58:59]
	global_load_dwordx4 v[34:37], v[36:37], off nt
	s_nop 0
	global_load_dwordx4 v[38:41], v[38:39], off nt
	s_mov_b64 s[16:17], 0x200
	s_mov_b64 s[22:23], 0x8000
	s_mov_b64 s[12:13], 0
	s_and_saveexec_b64 s[36:37], s[8:9]
	s_xor_b64 s[8:9], exec, s[36:37]
	s_cbranch_execz .LBB0_379
	s_and_b64 vcc, exec, s[10:11]
	s_cbranch_vccz .LBB0_377
	v_mul_u32_u24_e32 v46, 0x600, v44
	s_mov_b64 s[12:13], -1
	s_branch .LBB0_378

; #define GAS __attribute__((address_space(1)))
; __device__ __forceinline__ void dn_load_raw(DnRaw& R, int unit, const bf16_t* DNR, const bf16_t* HALO, const float* GBT, int tid) {
;     ...
;         for (int j = 0; j < 5; ++j) { const int t = t0 - 3 + j; v4u w4 = (v4u){0u, 0u, 0u, 0u};
;             if (t >= 0) w4 = *(const GAS v4u*)(region + part * 8192 + t * 128 + 8 * cg);
;             else if (n != 0) w4 = *(const GAS v4u*)(HALO + (size_t)(rb - 1) * 4608 + (t + 3) * 1536 + h * 384 + part * 128 + 8 * cg);
;             R.w[part][j] = w4; }
.LBB0_379:
	s_or_saveexec_b64 s[8:9], s[8:9]
	v_lshl_add_u64 v[62:63], v[50:51], 0, s[16:17]
	v_lshl_add_u64 v[60:61], v[42:43], 0, s[22:23]
	v_mov_b64_e32 v[48:49], v[62:63]
	s_xor_b64 exec, exec, s[8:9]
	s_or_b64 s[12:13], s[12:13], exec
	v_mov_b64_e32 v[48:49], v[60:61]
	s_or_b64 exec, exec, s[8:9]
	v_mov_b32_e32 v42, 0
	v_mov_b32_e32 v43, v42
	v_mov_b32_e32 v44, v42
	v_mov_b32_e32 v45, v42
	s_and_saveexec_b64 s[8:9], s[12:13]
	s_cbranch_execz .LBB0_383
	v_mov_b32_e32 v47, v42
	v_lshl_add_u64 v[42:43], v[46:47], 1, v[48:49]
	global_load_dwordx4 v[42:45], v[42:43], off nt

; #define GAS __attribute__((address_space(1)))
; __device__ __forceinline__ void dn_load_raw(DnRaw& R, int unit, const bf16_t* DNR, const bf16_t* HALO, const float* GBT, int tid) {
;     ...
;         for (int j = 0; j < 5; ++j) { const int t = t0 - 3 + j; v4u w4 = (v4u){0u, 0u, 0u, 0u};
;             if (t >= 0) w4 = *(const GAS v4u*)(region + part * 8192 + t * 128 + 8 * cg);
;             else if (n != 0) w4 = *(const GAS v4u*)(HALO + (size_t)(rb - 1) * 4608 + (t + 3) * 1536 + h * 384 + part * 128 + 8 * cg);
;             R.w[part][j] = w4; }
.LBB0_388:
	s_andn2_saveexec_b64 s[12:13], s[12:13]
	s_or_b64 s[8:9], s[8:9], exec
	v_mov_b64_e32 v[62:63], v[60:61]
	s_or_b64 exec, exec, s[12:13]
	v_mov_b32_e32 v46, 0
	v_mov_b32_e32 v47, v46
	v_mov_b32_e32 v48, v46
	v_mov_b32_e32 v49, v46
	s_and_saveexec_b64 s[12:13], s[8:9]
	s_cbranch_execz .LBB0_392
	v_mov_b32_e32 v53, v46
	v_lshl_add_u64 v[46:47], v[52:53], 1, v[62:63]
	global_load_dwordx4 v[46:49], v[46:47], off nt

; #define GAS __attribute__((address_space(1)))
; __device__ __forceinline__ void dn_load_raw(DnRaw& R, int unit, const bf16_t* DNR, const bf16_t* HALO, const float* GBT, int tid) {
;     ...
;         for (int j = 0; j < 5; ++j) { const int t = t0 - 3 + j; v4u w4 = (v4u){0u, 0u, 0u, 0u};
;             if (t >= 0) w4 = *(const GAS v4u*)(region + part * 8192 + t * 128 + 8 * cg);
;             else if (n != 0) w4 = *(const GAS v4u*)(HALO + (size_t)(rb - 1) * 4608 + (t + 3) * 1536 + h * 384 + part * 128 + 8 * cg);
;             R.w[part][j] = w4; }
;     R.be = 0.f; R.gg = 0.f;
;     if (tid < 64) { const int m = rb * 64 + tid; R.be = GBT[(size_t)m * 8 + h]; R.gg = GBT[(size_t)m * 8 + 4 + h]; }
.LBB0_397:
	s_andn2_saveexec_b64 s[6:7], s[6:7]
	v_mov_b32_e32 v55, 0
	v_lshl_add_u64 v[62:63], v[54:55], 1, v[60:61]
	s_or_b64 s[8:9], s[8:9], exec
	s_or_b64 exec, exec, s[6:7]
	v_mov_b32_e32 v66, 0
	v_mov_b32_e32 v67, v66
	v_mov_b32_e32 v68, v66
	v_mov_b32_e32 v69, v66
	v_mov_b64_e32 v[50:51], v[66:67]
	v_mov_b64_e32 v[52:53], v[68:69]
	s_and_saveexec_b64 s[6:7], s[8:9]
	s_cbranch_execz .LBB0_401
	global_load_dwordx4 v[50:53], v[62:63], off nt
.LBB0_401:
	s_or_b64 exec, exec, s[6:7]
	v_mov_b32_e32 v57, v66
	v_lshl_add_u64 v[62:63], v[60:61], 0, v[56:57]
	v_mov_b32_e32 v59, v66
	v_lshl_add_u64 v[64:65], v[60:61], 0, v[58:59]
	global_load_dwordx4 v[54:57], v[62:63], off nt
	global_load_dwordx4 v[58:61], v[64:65], off nt
	s_add_u32 s16, s60, 0x100000
	s_addc_u32 s17, s61, 0
	v_cmp_gt_u32_e32 vcc, 64, v0
	v_mov_b32_e32 v67, 0
	s_and_saveexec_b64 s[6:7], vcc
	s_cbranch_execz .LBB0_404
	v_lshl_or_b32 v62, s33, 6, v0
	v_ashrrev_i32_e32 v63, 31, v62
	v_lshlrev_b64 v[62:63], 5, v[62:63]
	v_lshl_add_u64 v[62:63], s[16:17], 0, v[62:63]
	s_lshl_b32 s8, s4, 2
	s_mov_b32 s9, 0
	v_lshl_add_u64 v[62:63], v[62:63], 0, s[8:9]
	global_load_dword v66, v[62:63], off nt
	global_load_dword v67, v[62:63], off offset:16 nt
	s_or_b64 exec, exec, s[6:7]
	s_cmpk_gt_i32 s2, 0x3ff
	s_cbranch_scc0 .LBB0_405

; #define GAS __attribute__((address_space(1)))
; __device__ __forceinline__ void hg_load_raw(HgRaw& R, const bf16_t* region, int tid) {
;     const int cg = tid & 15, t0 = 2 * (tid >> 4);
; #pragma unroll
;     for (int part = 0; part < 3; ++part)
; #pragma unroll
;         for (int rr = 0; rr < 2; ++rr) R.w[part][rr] = *(const GAS v4u*)(region + part * 8192 + (t0 + rr) * 128 + 8 * cg);
; }
; __global__ void __launch_bounds__(NWAVES * 64, 2) fwd(Args args) {
;     ...
;             { HgRaw H; hg_load_raw(H, HGR + (size_t)blockIdx.x * 32768, tid);
;               for (int u = (int)blockIdx.x; u < 1024; u += G) p2_hg_unit(lds, HGR + (size_t)u * 32768, OLH + (size_t)u * 8192, DEC + (size_t)u * 128, tid, lane, wave, H, (u + G < 1024) ? HGR + (size_t)(u + G) * 32768 : nullptr); }
.LBB0_405:
	s_mov_b32 s7, 0
	s_mov_b32 s6, s2
	s_lshl_b64 s[6:7], s[6:7], 16
	s_add_u32 s6, s26, s6
	s_addc_u32 s7, s27, s7
	v_mov_b32_e32 v113, 0
	v_lshlrev_b32_e32 v1, 8, v1
	v_lshl_add_u64 v[62:63], s[6:7], 0, v[112:113]
	s_mov_b64 s[6:7], 0x8000
	v_or_b32_e32 v112, 0x100, v1
	v_and_b32_e32 v70, 0x3e00, v1
	v_mov_b32_e32 v71, v113
	s_mov_b64 s[8:9], 0x4000
	v_lshl_add_u64 v[64:65], v[62:63], 0, s[6:7]
	v_lshl_add_u64 v[72:73], v[62:63], 0, s[8:9]
	v_lshl_add_u64 v[76:77], v[62:63], 0, v[112:113]
	v_lshl_add_u64 v[62:63], v[62:63], 0, v[70:71]
	v_lshl_add_u64 v[74:75], v[72:73], 0, v[112:113]
	v_lshl_add_u64 v[72:73], v[72:73], 0, v[70:71]
	global_load_dwordx4 v[96:99], v[76:77], off nt
	global_load_dwordx4 v[100:103], v[62:63], off nt
	global_load_dwordx4 v[104:107], v[74:75], off nt
	global_load_dwordx4 v[108:111], v[72:73], off nt
	v_lshl_add_u64 v[62:63], v[64:65], 0, v[70:71]
	v_lshl_add_u64 v[68:69], v[64:65], 0, v[112:113]
	global_load_dwordx4 v[92:95], v[62:63], off nt
	global_load_dwordx4 v[88:91], v[68:69], off nt
	s_cmp_eq_u64 s[60:61], 0
	s_cselect_b64 s[44:45], -1, 0
	s_ashr_i32 s35, s34, 31
	s_lshl_b64 s[42:43], s[2:3], 9
	s_lshl_b64 s[12:13], s[2:3], 14
	s_lshl_b64 s[22:23], s[34:35], 9
	s_add_u32 s74, s12, 0xe000000
	v_writelane_b32 v240, s66, 24
	s_movk_i32 s33, 0x220
	s_mov_b32 s66, 0x180000
	s_movk_i32 s67, 0x880
	s_movk_i32 s69, 0x110
	s_movk_i32 s70, 0x90
	s_mov_b32 s71, 0xffffff0
	s_mov_b32 s72, 0x6000000
	s_mov_b32 s73, 0x6004000
	s_mov_b64 s[10:11], s[14:15]
	s_mov_b32 s40, s2
	s_mov_b64 s[46:47], s[42:43]
	s_addc_u32 s75, s13, 0
	s_lshl_b64 s[36:37], s[34:35], 14
	s_lshl_b64 s[38:39], s[34:35], 16
	s_add_i32 s76, 0, 0x13c00
	s_add_i32 s77, 0, 0x17e00
	s_add_i32 s78, 0, 0x1c200
	s_add_i32 s68, 0, 0x11800
	s_waitcnt vmcnt(5)
	v_mov_b64_e32 v[68:69], v[96:97]
	s_waitcnt vmcnt(4)
	v_mov_b64_e32 v[62:63], v[100:101]
	s_waitcnt vmcnt(3)
	v_mov_b64_e32 v[76:77], v[104:105]
	s_waitcnt vmcnt(2)
	v_mov_b64_e32 v[72:73], v[108:109]
	v_mov_b64_e32 v[64:65], v[102:103]
	s_waitcnt vmcnt(1)
	v_mov_b64_e32 v[80:81], v[92:93]
	s_waitcnt vmcnt(0)
	v_mov_b64_e32 v[84:85], v[88:89]
	v_mov_b64_e32 v[70:71], v[98:99]
	v_mov_b64_e32 v[74:75], v[110:111]
	v_mov_b64_e32 v[78:79], v[106:107]
	v_mov_b64_e32 v[82:83], v[94:95]
	v_mov_b64_e32 v[86:87], v[90:91]
	s_branch .LBB0_407

; #define GAS __attribute__((address_space(1)))
; __device__ __forceinline__ void hg_load_raw(HgRaw& R, const bf16_t* region, int tid) {
;     const int cg = tid & 15, t0 = 2 * (tid >> 4);
; #pragma unroll
;     for (int part = 0; part < 3; ++part)
; #pragma unroll
;         for (int rr = 0; rr < 2; ++rr) R.w[part][rr] = *(const GAS v4u*)(region + part * 8192 + (t0 + rr) * 128 + 8 * cg);
; }
; __device__ __forceinline__ void p2_hg_unit(LAS unsigned char* lds, bf16_t* region, bf16_t* oloc, float* dec, int tid_in, int lane_in, int wave_in, HgRaw& R, const bf16_t* next_region, const bool ST = true) {
;     ...
;     if (next_region) hg_load_raw(R, next_region, tid);
.LBB0_407:
	s_add_i32 s40, s40, s34
	s_cmpk_gt_i32 s40, 0x3ff
	s_cselect_b64 s[48:49], -1, 0
	v_mov_b32_e32 v114, v0
	s_or_b64 s[48:49], s[48:49], s[44:45]
	s_and_b64 vcc, exec, s[48:49]
	v_readfirstlane_b32 s4, v114
	s_cbranch_vccnz .LBB0_409
	s_ashr_i32 s41, s40, 31
	s_lshl_b64 s[48:49], s[40:41], 16
	v_lshlrev_b32_e32 v1, 4, v114
	s_add_u32 s48, s26, s48
	v_and_b32_e32 v62, 0xffffff00, v1
	s_addc_u32 s49, s27, s49
	v_and_b32_e32 v112, 0xf0, v1
	v_ashrrev_i32_e32 v63, 31, v62
	v_or_b32_e32 v72, 0x80, v62
	v_lshl_add_u64 v[80:81], s[48:49], 0, v[112:113]
	v_lshlrev_b64 v[82:83], 1, v[62:63]
	v_ashrrev_i32_e32 v73, 31, v72
	v_lshl_add_u64 v[68:69], v[80:81], 0, v[82:83]
	v_lshl_add_u64 v[74:75], v[80:81], 0, s[8:9]
	v_lshlrev_b64 v[84:85], 1, v[72:73]
	v_lshl_add_u64 v[80:81], v[80:81], 0, s[6:7]
	v_lshl_add_u64 v[76:77], v[74:75], 0, v[82:83]
	v_lshl_add_u64 v[78:79], v[74:75], 0, v[84:85]
	v_lshl_add_u64 v[82:83], v[80:81], 0, v[82:83]
	v_lshl_add_u64 v[84:85], v[80:81], 0, v[84:85]
	global_load_dwordx4 v[62:65], v[68:69], off nt
	s_nop 0
	global_load_dwordx4 v[68:71], v[68:69], off offset:256 nt
	s_nop 0
	global_load_dwordx4 v[72:75], v[76:77], off nt
	s_nop 0
	global_load_dwordx4 v[76:79], v[78:79], off nt
	s_nop 0
	global_load_dwordx4 v[80:83], v[82:83], off nt
	s_nop 0
	global_load_dwordx4 v[84:87], v[84:85], off nt

; #define GAS __attribute__((address_space(1)))
; __device__ __forceinline__ void dn_load_raw(DnRaw& R, int unit, const bf16_t* DNR, const bf16_t* HALO, const float* GBT, int tid) {
;     ...
;         for (int j = 0; j < 5; ++j) { const int t = t0 - 3 + j; v4u w4 = (v4u){0u, 0u, 0u, 0u};
;             if (t >= 0) w4 = *(const GAS v4u*)(region + part * 8192 + t * 128 + 8 * cg);
;             else if (n != 0) w4 = *(const GAS v4u*)(HALO + (size_t)(rb - 1) * 4608 + (t + 3) * 1536 + h * 384 + part * 128 + 8 * cg);
;             R.w[part][j] = w4; }
.LBB0_431:
	s_or_saveexec_b64 s[50:51], s[50:51]
	v_add_u32_e32 v2, -3, v73
	v_lshl_add_u64 v[42:43], s[6:7], 0, v[62:63]
	v_lshlrev_b32_e32 v44, 7, v2
	s_xor_b64 exec, exec, s[50:51]
	v_mov_b32_e32 v45, v63
	v_lshl_add_u64 v[6:7], v[44:45], 1, v[42:43]
	s_or_b64 s[8:9], s[8:9], exec
	s_or_b64 exec, exec, s[50:51]
	v_mov_b32_e32 v62, v63
	v_mov_b32_e32 v64, v63
	v_mov_b32_e32 v65, v63
	v_mov_b64_e32 v[2:3], v[62:63]
	v_mov_b64_e32 v[4:5], v[64:65]
	s_and_saveexec_b64 s[6:7], s[8:9]
	s_cbranch_execz .LBB0_435
	global_load_dwordx4 v[2:5], v[6:7], off nt

; #define GAS __attribute__((address_space(1)))
; __device__ __forceinline__ void dn_load_raw(DnRaw& R, int unit, const bf16_t* DNR, const bf16_t* HALO, const float* GBT, int tid) {
;     ...
;         for (int j = 0; j < 5; ++j) { const int t = t0 - 3 + j; v4u w4 = (v4u){0u, 0u, 0u, 0u};
;             if (t >= 0) w4 = *(const GAS v4u*)(region + part * 8192 + t * 128 + 8 * cg);
;             else if (n != 0) w4 = *(const GAS v4u*)(HALO + (size_t)(rb - 1) * 4608 + (t + 3) * 1536 + h * 384 + part * 128 + 8 * cg);
;             R.w[part][j] = w4; }
.LBB0_440:
	s_or_saveexec_b64 s[50:51], s[50:51]
	v_add_u32_e32 v6, -2, v73
	v_lshlrev_b32_e32 v46, 7, v6
	s_xor_b64 exec, exec, s[50:51]
	v_mov_b32_e32 v47, v63
	v_lshl_add_u64 v[10:11], v[46:47], 1, v[42:43]
	s_or_b64 s[6:7], s[6:7], exec
	s_or_b64 exec, exec, s[50:51]
	v_mov_b32_e32 v62, v63
	v_mov_b32_e32 v64, v63
	v_mov_b32_e32 v65, v63
	v_mov_b64_e32 v[6:7], v[62:63]
	v_mov_b64_e32 v[8:9], v[64:65]
	s_and_saveexec_b64 s[50:51], s[6:7]
	s_cbranch_execz .LBB0_444
	global_load_dwordx4 v[6:9], v[10:11], off nt

; #define GAS __attribute__((address_space(1)))
; __device__ __forceinline__ void dn_load_raw(DnRaw& R, int unit, const bf16_t* DNR, const bf16_t* HALO, const float* GBT, int tid) {
;     ...
; #pragma unroll
;     for (int part = 0; part < 3; ++part)
; #pragma unroll
;         for (int j = 0; j < 5; ++j) { const int t = t0 - 3 + j; v4u w4 = (v4u){0u, 0u, 0u, 0u};
;             if (t >= 0) w4 = *(const GAS v4u*)(region + part * 8192 + t * 128 + 8 * cg);
;             else if (n != 0) w4 = *(const GAS v4u*)(HALO + (size_t)(rb - 1) * 4608 + (t + 3) * 1536 + h * 384 + part * 128 + 8 * cg);
;             R.w[part][j] = w4; }
.LBB0_449:
	s_or_saveexec_b64 s[50:51], s[50:51]
	v_add_u32_e32 v10, -1, v73
	v_lshlrev_b32_e32 v50, 7, v10
	s_xor_b64 exec, exec, s[50:51]
	v_mov_b32_e32 v51, v63
	v_lshl_add_u64 v[14:15], v[50:51], 1, v[42:43]
	s_or_b64 s[6:7], s[6:7], exec
	s_or_b64 exec, exec, s[50:51]
	v_mov_b32_e32 v62, v63
	v_mov_b32_e32 v64, v63
	v_mov_b32_e32 v65, v63
	v_mov_b64_e32 v[10:11], v[62:63]
	v_mov_b64_e32 v[12:13], v[64:65]
	s_and_saveexec_b64 s[50:51], s[6:7]
	s_cbranch_execz .LBB0_453
	global_load_dwordx4 v[10:13], v[14:15], off nt

; #define GAS __attribute__((address_space(1)))
; __device__ __forceinline__ void dn_load_raw(DnRaw& R, int unit, const bf16_t* DNR, const bf16_t* HALO, const float* GBT, int tid) {
;     ...
; #pragma unroll
;     for (int part = 0; part < 3; ++part)
; #pragma unroll
;         for (int j = 0; j < 5; ++j) { const int t = t0 - 3 + j; v4u w4 = (v4u){0u, 0u, 0u, 0u};
;             if (t >= 0) w4 = *(const GAS v4u*)(region + part * 8192 + t * 128 + 8 * cg);
;             else if (n != 0) w4 = *(const GAS v4u*)(HALO + (size_t)(rb - 1) * 4608 + (t + 3) * 1536 + h * 384 + part * 128 + 8 * cg);
;             R.w[part][j] = w4; }
.LBB0_458:
	s_or_saveexec_b64 s[66:67], s[66:67]
	v_lshlrev_b32_e32 v54, 7, v73
	s_xor_b64 exec, exec, s[66:67]
	v_mov_b32_e32 v55, v63
	v_lshl_add_u64 v[18:19], v[54:55], 1, v[42:43]
	s_or_b64 s[50:51], s[50:51], exec
	s_or_b64 exec, exec, s[66:67]
	v_mov_b32_e32 v62, v63
	v_mov_b32_e32 v64, v63
	v_mov_b32_e32 v65, v63
	v_mov_b64_e32 v[14:15], v[62:63]
	v_mov_b64_e32 v[16:17], v[64:65]
	s_and_saveexec_b64 s[66:67], s[50:51]
	s_cbranch_execz .LBB0_462
	global_load_dwordx4 v[14:17], v[18:19], off nt

; #define GAS __attribute__((address_space(1)))
; __device__ __forceinline__ void dn_load_raw(DnRaw& R, int unit, const bf16_t* DNR, const bf16_t* HALO, const float* GBT, int tid) {
;     ...
; #pragma unroll
;     for (int part = 0; part < 3; ++part)
; #pragma unroll
;         for (int j = 0; j < 5; ++j) { const int t = t0 - 3 + j; v4u w4 = (v4u){0u, 0u, 0u, 0u};
;             if (t >= 0) w4 = *(const GAS v4u*)(region + part * 8192 + t * 128 + 8 * cg);
;             else if (n != 0) w4 = *(const GAS v4u*)(HALO + (size_t)(rb - 1) * 4608 + (t + 3) * 1536 + h * 384 + part * 128 + 8 * cg);
;             R.w[part][j] = w4; }
.LBB0_467:
	s_or_saveexec_b64 s[66:67], s[66:67]
	v_lshlrev_b32_e32 v60, 7, v74
	s_xor_b64 exec, exec, s[66:67]
	v_mov_b32_e32 v61, v63
	v_lshl_add_u64 v[22:23], v[60:61], 1, v[42:43]
	s_or_b64 s[50:51], s[50:51], exec
	s_or_b64 exec, exec, s[66:67]
	v_mov_b32_e32 v62, v63
	v_mov_b32_e32 v64, v63
	v_mov_b32_e32 v65, v63
	v_mov_b64_e32 v[18:19], v[62:63]
	v_mov_b64_e32 v[20:21], v[64:65]
	s_and_saveexec_b64 s[66:67], s[50:51]
	s_cbranch_execz .LBB0_471
	global_load_dwordx4 v[18:21], v[22:23], off nt

; #define GAS __attribute__((address_space(1)))
; __device__ __forceinline__ void dn_load_raw(DnRaw& R, int unit, const bf16_t* DNR, const bf16_t* HALO, const float* GBT, int tid) {
;     ...
; #pragma unroll
;     for (int part = 0; part < 3; ++part)
; #pragma unroll
;         for (int j = 0; j < 5; ++j) { const int t = t0 - 3 + j; v4u w4 = (v4u){0u, 0u, 0u, 0u};
;             if (t >= 0) w4 = *(const GAS v4u*)(region + part * 8192 + t * 128 + 8 * cg);
;             else if (n != 0) w4 = *(const GAS v4u*)(HALO + (size_t)(rb - 1) * 4608 + (t + 3) * 1536 + h * 384 + part * 128 + 8 * cg);
;             R.w[part][j] = w4; }
.LBB0_476:
	s_or_saveexec_b64 s[66:67], s[66:67]
	s_mov_b64 s[94:95], 0x4000
	v_lshl_add_u64 v[38:39], v[42:43], 0, s[94:95]
	s_xor_b64 exec, exec, s[66:67]
	v_mov_b32_e32 v45, v63
	v_lshl_add_u64 v[26:27], v[44:45], 1, v[38:39]
	s_or_b64 s[50:51], s[50:51], exec
	s_or_b64 exec, exec, s[66:67]
	v_mov_b32_e32 v62, v63
	v_mov_b32_e32 v64, v63
	v_mov_b32_e32 v65, v63
	v_mov_b64_e32 v[22:23], v[62:63]
	v_mov_b64_e32 v[24:25], v[64:65]
	s_and_saveexec_b64 s[66:67], s[50:51]
	s_cbranch_execz .LBB0_480
	global_load_dwordx4 v[22:25], v[26:27], off nt

; #define GAS __attribute__((address_space(1)))
; __device__ __forceinline__ void dn_load_raw(DnRaw& R, int unit, const bf16_t* DNR, const bf16_t* HALO, const float* GBT, int tid) {
;     ...
; #pragma unroll
;     for (int part = 0; part < 3; ++part)
; #pragma unroll
;         for (int j = 0; j < 5; ++j) { const int t = t0 - 3 + j; v4u w4 = (v4u){0u, 0u, 0u, 0u};
;             if (t >= 0) w4 = *(const GAS v4u*)(region + part * 8192 + t * 128 + 8 * cg);
;             else if (n != 0) w4 = *(const GAS v4u*)(HALO + (size_t)(rb - 1) * 4608 + (t + 3) * 1536 + h * 384 + part * 128 + 8 * cg);
;             R.w[part][j] = w4; }
.LBB0_485:
	s_andn2_saveexec_b64 s[66:67], s[66:67]
	v_mov_b32_e32 v47, v63
	v_lshl_add_u64 v[30:31], v[46:47], 1, v[38:39]
	s_or_b64 s[50:51], s[50:51], exec
	s_or_b64 exec, exec, s[66:67]
	v_mov_b32_e32 v62, v63
	v_mov_b32_e32 v64, v63
	v_mov_b32_e32 v65, v63
	v_mov_b64_e32 v[26:27], v[62:63]
	v_mov_b64_e32 v[28:29], v[64:65]
	s_and_saveexec_b64 s[66:67], s[50:51]
	s_cbranch_execz .LBB0_489
	global_load_dwordx4 v[26:29], v[30:31], off nt

; #define GAS __attribute__((address_space(1)))
; __device__ __forceinline__ void dn_load_raw(DnRaw& R, int unit, const bf16_t* DNR, const bf16_t* HALO, const float* GBT, int tid) {
;     ...
; #pragma unroll
;     for (int part = 0; part < 3; ++part)
; #pragma unroll
;         for (int j = 0; j < 5; ++j) { const int t = t0 - 3 + j; v4u w4 = (v4u){0u, 0u, 0u, 0u};
;             if (t >= 0) w4 = *(const GAS v4u*)(region + part * 8192 + t * 128 + 8 * cg);
;             else if (n != 0) w4 = *(const GAS v4u*)(HALO + (size_t)(rb - 1) * 4608 + (t + 3) * 1536 + h * 384 + part * 128 + 8 * cg);
;             R.w[part][j] = w4; }
.LBB0_494:
	s_andn2_saveexec_b64 s[66:67], s[66:67]
	v_mov_b32_e32 v51, v63
	v_lshl_add_u64 v[34:35], v[50:51], 1, v[38:39]
	s_or_b64 s[50:51], s[50:51], exec
	s_or_b64 exec, exec, s[66:67]
	v_mov_b32_e32 v62, v63
	v_mov_b32_e32 v64, v63
	v_mov_b32_e32 v65, v63
	v_mov_b64_e32 v[30:31], v[62:63]
	v_mov_b64_e32 v[32:33], v[64:65]
	s_and_saveexec_b64 s[66:67], s[50:51]
	s_cbranch_execz .LBB0_498
	global_load_dwordx4 v[30:33], v[34:35], off nt

; #define GAS __attribute__((address_space(1)))
; __device__ __forceinline__ void dn_load_raw(DnRaw& R, int unit, const bf16_t* DNR, const bf16_t* HALO, const float* GBT, int tid) {
;     ...
; #pragma unroll
;     for (int part = 0; part < 3; ++part)
; #pragma unroll
;         for (int j = 0; j < 5; ++j) { const int t = t0 - 3 + j; v4u w4 = (v4u){0u, 0u, 0u, 0u};
;             if (t >= 0) w4 = *(const GAS v4u*)(region + part * 8192 + t * 128 + 8 * cg);
;             else if (n != 0) w4 = *(const GAS v4u*)(HALO + (size_t)(rb - 1) * 4608 + (t + 3) * 1536 + h * 384 + part * 128 + 8 * cg);
;             R.w[part][j] = w4; }
.LBB0_503:
	s_andn2_saveexec_b64 s[66:67], s[66:67]
	v_mov_b32_e32 v55, v63
	v_lshl_add_u64 v[40:41], v[54:55], 1, v[38:39]
	s_or_b64 s[50:51], s[50:51], exec
	s_or_b64 exec, exec, s[66:67]
	v_mov_b32_e32 v62, v63
	v_mov_b32_e32 v64, v63
	v_mov_b32_e32 v65, v63
	v_mov_b64_e32 v[34:35], v[62:63]
	v_mov_b64_e32 v[36:37], v[64:65]
	s_and_saveexec_b64 s[66:67], s[50:51]
	s_cbranch_execz .LBB0_507
	global_load_dwordx4 v[34:37], v[40:41], off nt

; #define GAS __attribute__((address_space(1)))
; __device__ __forceinline__ void dn_load_raw(DnRaw& R, int unit, const bf16_t* DNR, const bf16_t* HALO, const float* GBT, int tid) {
;     ...
; #pragma unroll
;     for (int part = 0; part < 3; ++part)
; #pragma unroll
;         for (int j = 0; j < 5; ++j) { const int t = t0 - 3 + j; v4u w4 = (v4u){0u, 0u, 0u, 0u};
;             if (t >= 0) w4 = *(const GAS v4u*)(region + part * 8192 + t * 128 + 8 * cg);
;             else if (n != 0) w4 = *(const GAS v4u*)(HALO + (size_t)(rb - 1) * 4608 + (t + 3) * 1536 + h * 384 + part * 128 + 8 * cg);
;             R.w[part][j] = w4; }
.LBB0_512:
	s_andn2_saveexec_b64 s[66:67], s[66:67]
	v_mov_b32_e32 v61, v63
	v_lshl_add_u64 v[48:49], v[60:61], 1, v[38:39]
	s_or_b64 s[50:51], s[50:51], exec
	s_or_b64 exec, exec, s[66:67]
	v_mov_b32_e32 v62, v63
	v_mov_b32_e32 v64, v63
	v_mov_b32_e32 v65, v63
	v_mov_b64_e32 v[38:39], v[62:63]
	v_mov_b64_e32 v[40:41], v[64:65]
	s_and_saveexec_b64 s[66:67], s[50:51]
	s_cbranch_execz .LBB0_516
	global_load_dwordx4 v[38:41], v[48:49], off nt

; #define GAS __attribute__((address_space(1)))
; __device__ __forceinline__ void dn_load_raw(DnRaw& R, int unit, const bf16_t* DNR, const bf16_t* HALO, const float* GBT, int tid) {
;     ...
; #pragma unroll
;     for (int part = 0; part < 3; ++part)
; #pragma unroll
;         for (int j = 0; j < 5; ++j) { const int t = t0 - 3 + j; v4u w4 = (v4u){0u, 0u, 0u, 0u};
;             if (t >= 0) w4 = *(const GAS v4u*)(region + part * 8192 + t * 128 + 8 * cg);
;             else if (n != 0) w4 = *(const GAS v4u*)(HALO + (size_t)(rb - 1) * 4608 + (t + 3) * 1536 + h * 384 + part * 128 + 8 * cg);
;             R.w[part][j] = w4; }
.LBB0_521:
	s_or_saveexec_b64 s[10:11], s[10:11]
	s_mov_b64 s[66:67], 0x8000
	v_lshl_add_u64 v[68:69], v[42:43], 0, s[66:67]
	s_xor_b64 exec, exec, s[10:11]
	v_mov_b32_e32 v45, v63
	v_lshl_add_u64 v[48:49], v[44:45], 1, v[68:69]
	s_or_b64 s[50:51], s[50:51], exec
	s_or_b64 exec, exec, s[10:11]
	v_mov_b32_e32 v62, v63
	v_mov_b32_e32 v64, v63
	v_mov_b32_e32 v65, v63
	v_mov_b64_e32 v[42:43], v[62:63]
	v_mov_b64_e32 v[44:45], v[64:65]
	s_and_saveexec_b64 s[10:11], s[50:51]
	s_cbranch_execz .LBB0_525
	global_load_dwordx4 v[42:45], v[48:49], off nt

; #define GAS __attribute__((address_space(1)))
; __device__ __forceinline__ void dn_load_raw(DnRaw& R, int unit, const bf16_t* DNR, const bf16_t* HALO, const float* GBT, int tid) {
;     ...
; #pragma unroll
;     for (int part = 0; part < 3; ++part)
; #pragma unroll
;         for (int j = 0; j < 5; ++j) { const int t = t0 - 3 + j; v4u w4 = (v4u){0u, 0u, 0u, 0u};
;             if (t >= 0) w4 = *(const GAS v4u*)(region + part * 8192 + t * 128 + 8 * cg);
;             else if (n != 0) w4 = *(const GAS v4u*)(HALO + (size_t)(rb - 1) * 4608 + (t + 3) * 1536 + h * 384 + part * 128 + 8 * cg);
;             R.w[part][j] = w4; }
.LBB0_530:
	s_andn2_saveexec_b64 s[50:51], s[50:51]
	v_mov_b32_e32 v47, v63
	v_lshl_add_u64 v[52:53], v[46:47], 1, v[68:69]
	s_or_b64 s[10:11], s[10:11], exec
	s_or_b64 exec, exec, s[50:51]
	v_mov_b32_e32 v62, v63
	v_mov_b32_e32 v64, v63
	v_mov_b32_e32 v65, v63
	v_mov_b64_e32 v[46:47], v[62:63]
	v_mov_b64_e32 v[48:49], v[64:65]
	s_and_saveexec_b64 s[50:51], s[10:11]
	s_cbranch_execz .LBB0_534
	global_load_dwordx4 v[46:49], v[52:53], off nt

; #define GAS __attribute__((address_space(1)))
; __device__ __forceinline__ void dn_load_raw(DnRaw& R, int unit, const bf16_t* DNR, const bf16_t* HALO, const float* GBT, int tid) {
;     ...
; #pragma unroll
;     for (int part = 0; part < 3; ++part)
; #pragma unroll
;         for (int j = 0; j < 5; ++j) { const int t = t0 - 3 + j; v4u w4 = (v4u){0u, 0u, 0u, 0u};
;             if (t >= 0) w4 = *(const GAS v4u*)(region + part * 8192 + t * 128 + 8 * cg);
;             else if (n != 0) w4 = *(const GAS v4u*)(HALO + (size_t)(rb - 1) * 4608 + (t + 3) * 1536 + h * 384 + part * 128 + 8 * cg);
;             R.w[part][j] = w4; }
.LBB0_539:
	s_andn2_saveexec_b64 s[8:9], s[8:9]
	v_mov_b32_e32 v51, v63
	v_lshl_add_u64 v[56:57], v[50:51], 1, v[68:69]
	s_or_b64 s[10:11], s[10:11], exec
	s_or_b64 exec, exec, s[8:9]
	v_mov_b32_e32 v62, v63
	v_mov_b32_e32 v64, v63
	v_mov_b32_e32 v65, v63
	v_mov_b64_e32 v[50:51], v[62:63]
	v_mov_b64_e32 v[52:53], v[64:65]
	s_and_saveexec_b64 s[8:9], s[10:11]
	s_cbranch_execz .LBB0_543
	global_load_dwordx4 v[50:53], v[56:57], off nt

; #define GAS __attribute__((address_space(1)))
; __device__ __forceinline__ void dn_load_raw(DnRaw& R, int unit, const bf16_t* DNR, const bf16_t* HALO, const float* GBT, int tid) {
;     ...
; #pragma unroll
;     for (int part = 0; part < 3; ++part)
; #pragma unroll
;         for (int j = 0; j < 5; ++j) { const int t = t0 - 3 + j; v4u w4 = (v4u){0u, 0u, 0u, 0u};
;             if (t >= 0) w4 = *(const GAS v4u*)(region + part * 8192 + t * 128 + 8 * cg);
;             else if (n != 0) w4 = *(const GAS v4u*)(HALO + (size_t)(rb - 1) * 4608 + (t + 3) * 1536 + h * 384 + part * 128 + 8 * cg);
;             R.w[part][j] = w4; }
.LBB0_548:
	s_andn2_saveexec_b64 s[10:11], s[10:11]
	v_mov_b32_e32 v55, v63
	v_lshl_add_u64 v[70:71], v[54:55], 1, v[68:69]
	s_or_b64 s[8:9], s[8:9], exec
	s_or_b64 exec, exec, s[10:11]
	v_mov_b32_e32 v62, v63
	v_mov_b32_e32 v64, v63
	v_mov_b32_e32 v65, v63
	v_mov_b64_e32 v[54:55], v[62:63]
	v_mov_b64_e32 v[56:57], v[64:65]
	s_and_saveexec_b64 s[10:11], s[8:9]
	s_cbranch_execz .LBB0_552
	global_load_dwordx4 v[54:57], v[70:71], off nt

; #define GAS __attribute__((address_space(1)))
; __device__ __forceinline__ void dn_load_raw(DnRaw& R, int unit, const bf16_t* DNR, const bf16_t* HALO, const float* GBT, int tid) {
;     ...
; #pragma unroll
;     for (int part = 0; part < 3; ++part)
; #pragma unroll
;         for (int j = 0; j < 5; ++j) { const int t = t0 - 3 + j; v4u w4 = (v4u){0u, 0u, 0u, 0u};
;             if (t >= 0) w4 = *(const GAS v4u*)(region + part * 8192 + t * 128 + 8 * cg);
;             else if (n != 0) w4 = *(const GAS v4u*)(HALO + (size_t)(rb - 1) * 4608 + (t + 3) * 1536 + h * 384 + part * 128 + 8 * cg);
;             R.w[part][j] = w4; }
;     R.be = 0.f; R.gg = 0.f;
;     if (tid < 64) { const int m = rb * 64 + tid; R.be = GBT[(size_t)m * 8 + h]; R.gg = GBT[(size_t)m * 8 + 4 + h]; }
.LBB0_557:
	s_andn2_saveexec_b64 s[6:7], s[6:7]
	v_mov_b32_e32 v61, v63
	v_lshl_add_u64 v[70:71], v[60:61], 1, v[68:69]
	s_or_b64 s[8:9], s[8:9], exec
	s_or_b64 exec, exec, s[6:7]
	v_mov_b32_e32 v62, v63
	v_mov_b32_e32 v64, v63
	v_mov_b32_e32 v65, v63
	v_mov_b64_e32 v[58:59], v[62:63]
	v_mov_b64_e32 v[60:61], v[64:65]
	s_and_saveexec_b64 s[6:7], s[8:9]
	s_cbranch_execz .LBB0_561
	global_load_dwordx4 v[58:61], v[70:71], off nt
.LBB0_561:
	s_or_b64 exec, exec, s[6:7]
	v_cmp_gt_i32_e32 vcc, 64, v96
	v_mov_b32_e32 v62, 0
	v_mov_b32_e32 v97, 0
	s_and_saveexec_b64 s[6:7], vcc
	s_cbranch_execz .LBB0_563
	v_lshl_add_u32 v64, s92, 6, v96
	v_ashrrev_i32_e32 v65, 31, v64
	v_lshlrev_b64 v[64:65], 5, v[64:65]
	v_lshl_add_u64 v[64:65], s[16:17], 0, v[64:65]
	s_lshl_b32 s42, s33, 2
	v_lshl_add_u64 v[64:65], v[64:65], 0, s[42:43]
	global_load_dword v97, v[64:65], off nt
	global_load_dword v62, v[64:65], off offset:16 nt

; #define GAS __attribute__((address_space(1)))
; __device__ __forceinline__ void p3_hg_scan(int job, bf16_t* HGR, const float* dec, int tid, const bool ST = true) {
;     const int bh = job >> 2, vt = 2 * (job & 3) + (tid >> 8), b = bh >> 2, h = bh & 3, kb = (tid >> 6) & 3, lane = tid & 63, g = lane >> 4;
;     const size_t eoff = 8192 + (size_t)((vt * 4 + kb) * 64 + lane) * 8; const int koff = 32 * kb + 4 * g;
;     f32x4 S0 = (f32x4){0.f, 0.f, 0.f, 0.f}, S1 = S0;
;     v4u bn[6]; f32x4 da[6], db[6];
; #pragma unroll
;     for (int u = 0; u < 6; ++u) { const int unit = (b * NCH + u) * 4 + h; bn[u] = *(const GAS v4u*)(HGR + (size_t)unit * 32768 + eoff); da[u] = *(const GAS f32x4*)(dec + (size_t)unit * 128 + koff); db[u] = *(const GAS f32x4*)(dec + (size_t)unit * 128 + koff + 16); }
.LBB0_660:
	s_load_dwordx16 s[68:83], s[0:1], 0x40
	s_waitcnt lgkmcnt(0)
	v_writelane_b32 v240, s68, 8
	s_nop 1
	v_writelane_b32 v240, s69, 9
	v_writelane_b32 v240, s70, 10
	v_writelane_b32 v240, s71, 11
	v_writelane_b32 v240, s72, 12
	v_writelane_b32 v240, s73, 13
	v_writelane_b32 v240, s74, 14
	v_writelane_b32 v240, s75, 15
	v_writelane_b32 v240, s76, 16
	v_writelane_b32 v240, s77, 17
	v_writelane_b32 v240, s78, 18
	v_writelane_b32 v240, s79, 19
	v_writelane_b32 v240, s80, 20
	v_writelane_b32 v240, s81, 21
	v_writelane_b32 v240, s82, 22
	v_writelane_b32 v240, s83, 23
	s_lshl_b32 s72, s2, 3
	s_lshr_b32 s73, s2, 3
	s_add_u32 s16, s60, 0x2e00000
	s_addc_u32 s17, s61, 0
	s_add_u32 s12, s60, 0x3800000
	s_addc_u32 s13, s61, 0
	s_add_u32 s22, s60, 0x2c00000
	s_addc_u32 s23, s61, 0
	s_add_u32 s14, s60, 0x3000000
	s_addc_u32 s15, s61, 0
	s_cmp_lt_i32 s56, 4
	s_cselect_b64 s[0:1], -1, 0
	s_cmp_gt_i32 s57, 3
	s_cselect_b64 s[6:7], -1, 0
	s_and_b64 s[0:1], s[0:1], s[6:7]
	s_andn2_b64 vcc, exec, s[0:1]
	s_cbranch_vccnz .LBB0_890
	s_cmp_gt_u32 s2, 31
	s_mov_b64 s[0:1], -1
	s_cbranch_scc0 .LBB0_673
	s_cmp_lt_u32 s2, 64
	s_cselect_b64 s[38:39], -1, 0
	s_cmp_gt_u32 s2, 63
	s_cbranch_scc1 .LBB0_678
	s_sub_i32 s0, s2, 32
	s_lshl_b32 s1, s0, 9
	v_bfe_u32 v1, v0, 6, 2
	s_waitcnt vmcnt(6)
	v_mov_b32_e32 v2, 0x700
	v_bitop3_b32 v2, s1, v2, v0 bitop3:0xc8
	v_lshlrev_b32_e32 v3, 6, v1
	v_or3_b32 v2, v2, v3, v234
	s_waitcnt vmcnt(2)
	v_lshlrev_b32_e32 v46, 4, v2
	v_mov_b32_e32 v47, 0
	v_lshl_add_u64 v[2:3], s[26:27], 0, v[46:47]
	s_mov_b64 s[6:7], 0x4000
	s_lshr_b32 s4, s0, 4
	v_lshl_add_u64 v[82:83], v[2:3], 0, s[6:7]
	v_and_b32_e32 v2, 48, v0
	s_bfe_u32 s3, s2, 0x20002
	s_lshl_b32 s0, s4, 9
	v_lshl_or_b32 v46, v1, 7, v2
	s_or_b32 s0, s0, s3
	s_mov_b32 s1, 0
	v_lshl_add_u64 v[2:3], s[60:61], 0, v[46:47]
	s_mov_b64 s[6:7], 0x180000
	v_lshl_add_u64 v[84:85], v[2:3], 0, s[6:7]
	s_lshl_b64 s[6:7], s[0:1], 16
	v_lshl_add_u64 v[2:3], v[82:83], 0, s[6:7]
	s_lshl_b64 s[6:7], s[0:1], 9
	v_lshl_add_u64 v[10:11], v[84:85], 0, s[6:7]
	s_or_b32 s6, s0, 4
	s_mov_b32 s7, s1
	s_lshl_b64 s[8:9], s[6:7], 16
	v_lshl_add_u64 v[14:15], v[82:83], 0, s[8:9]
	s_lshl_b64 s[6:7], s[6:7], 9
	global_load_dwordx4 v[6:9], v[2:3], off nt
	s_nop 0
	global_load_dwordx4 v[2:5], v[10:11], off nt
	s_nop 0
	global_load_dwordx4 v[10:13], v[10:11], off offset:64 nt
	s_nop 0
	global_load_dwordx4 v[66:69], v[14:15], off nt
	v_lshl_add_u64 v[14:15], v[84:85], 0, s[6:7]
	s_or_b32 s6, s0, 8
	s_mov_b32 s7, s1
	s_lshl_b64 s[8:9], s[6:7], 16
	s_lshl_b64 s[6:7], s[6:7], 9
	v_lshl_add_u64 v[18:19], v[84:85], 0, s[6:7]
	s_or_b32 s6, s0, 12
	s_mov_b32 s7, s1
	global_load_dwordx4 v[54:57], v[14:15], off nt
	global_load_dwordx4 v[62:65], v[14:15], off offset:64 nt
	v_lshl_add_u64 v[14:15], v[82:83], 0, s[8:9]
	s_lshl_b64 s[8:9], s[6:7], 16
	s_lshl_b64 s[6:7], s[6:7], 9
	v_lshl_add_u64 v[22:23], v[84:85], 0, s[6:7]
	s_or_b32 s6, s0, 16
	s_mov_b32 s7, s1
	v_lshl_add_u64 v[20:21], v[82:83], 0, s[8:9]
	s_lshl_b64 s[8:9], s[6:7], 16
	s_lshl_b64 s[6:7], s[6:7], 9
	s_or_b32 s0, s0, 20
	v_lshl_add_u64 v[34:35], v[84:85], 0, s[6:7]
	s_lshl_b64 s[6:7], s[0:1], 16
	v_lshl_add_u64 v[36:37], v[82:83], 0, s[6:7]
	s_lshl_b64 s[6:7], s[0:1], 9
	v_lshl_add_u64 v[30:31], v[82:83], 0, s[8:9]
	v_lshl_add_u64 v[38:39], v[84:85], 0, s[6:7]
	global_load_dwordx4 v[58:61], v[14:15], off nt
	s_nop 0
	global_load_dwordx4 v[14:17], v[18:19], off nt
	global_load_dwordx4 v[26:29], v[18:19], off offset:64 nt
	global_load_dwordx4 v[50:53], v[20:21], off nt
	s_nop 0
	global_load_dwordx4 v[18:21], v[22:23], off nt
	s_nop 0
	global_load_dwordx4 v[22:25], v[22:23], off offset:64 nt
	s_nop 0
	global_load_dwordx4 v[70:73], v[30:31], off nt
	s_nop 0
	global_load_dwordx4 v[30:33], v[34:35], off nt
	global_load_dwordx4 v[42:45], v[34:35], off offset:64 nt
	global_load_dwordx4 v[74:77], v[36:37], off nt
	s_nop 0
	global_load_dwordx4 v[34:37], v[38:39], off nt
	s_nop 0
	global_load_dwordx4 v[38:41], v[38:39], off offset:64 nt
	v_mov_b32_e32 v48, v47
	v_mov_b32_e32 v49, v47
	s_lshl_b32 s4, s4, 7
	v_mov_b32_e32 v46, v47
	v_mov_b64_e32 v[80:81], v[48:49]
	s_or_b32 s4, s4, 6
	s_mov_b32 s8, 5
	s_mov_b32 s6, s0
	v_mov_b64_e32 v[78:79], v[46:47]
	s_branch .LBB0_665

; #define GAS __attribute__((address_space(1)))
; __device__ __forceinline__ unsigned pk2(float lo, float hi) { const f32x2_t v = {lo, hi}; return __builtin_bit_cast(unsigned, __builtin_convertvector(v, bf16x2_t)); }
; __device__ __forceinline__ void p3_hg_scan(int job, bf16_t* HGR, const float* dec, int tid, const bool ST = true) {
;     ...
;     for (int n0 = 0; n0 < NCH; n0 += 6) {
; #pragma unroll
;         for (int u = 0; u < 6; ++u) { const int n = n0 + u; if (n < NCH) { const int unit = (b * NCH + n) * 4 + h;
;             const v4u bv = bn[u]; const f32x4 dva = da[u], dvb = db[u];
;             const int nn = (n + 6 < NCH) ? n + 6 : NCH - 1; const int unit2 = (b * NCH + nn) * 4 + h;
;             bn[u] = *(const GAS v4u*)(HGR + (size_t)unit2 * 32768 + eoff); da[u] = *(const GAS f32x4*)(dec + (size_t)unit2 * 128 + koff); db[u] = *(const GAS f32x4*)(dec + (size_t)unit2 * 128 + koff + 16);
;             f32x4 b0, b1; unpack8(bv, b0, b1);
;             const f32x4 Sn0 = S0 * dva + b0, Sn1 = S1 * dvb + b1;
;             asm volatile("" :: "v"(Sn0[0]), "v"(Sn0[1]), "v"(Sn0[2]), "v"(Sn0[3]), "v"(Sn1[0]), "v"(Sn1[1]), "v"(Sn1[2]), "v"(Sn1[3]) : "memory");
;             if (ST) *(GAS v4u*)(HGR + (size_t)unit * 32768 + eoff) = (v4u){pk2(S0[0], S0[1]), pk2(S0[2], S0[3]), pk2(S1[0], S1[1]), pk2(S1[2], S1[3])};
;             S0 = Sn0; S1 = Sn1; } }
.LBB0_665:
	s_add_i32 s9, s8, -5
	s_min_u32 s0, s9, 0x79
	s_add_i32 s0, s0, s4
	s_lshl_b32 s0, s0, 2
	s_waitcnt vmcnt(1)
	v_mov_b64_e32 v[88:89], v[64:65]
	s_or_b32 s0, s0, s3
	v_mov_b64_e32 v[86:87], v[62:63]
	v_mov_b64_e32 v[64:65], v[4:5]
	s_lshl_b64 s[10:11], s[0:1], 16
	v_mov_b32_e32 v1, v69
	v_mov_b32_e32 v102, v68
	v_mov_b32_e32 v103, v67
	v_mov_b32_e32 v104, v66
	v_mov_b64_e32 v[68:69], v[12:13]
	v_mov_b64_e32 v[62:63], v[2:3]
	v_lshl_add_u64 v[2:3], v[82:83], 0, s[10:11]
	s_lshl_b64 s[10:11], s[0:1], 9
	s_sub_i32 s0, s6, 20
	v_mov_b64_e32 v[66:67], v[10:11]
	v_lshl_add_u64 v[10:11], v[84:85], 0, s[10:11]
	s_lshl_b64 s[10:11], s[0:1], 16
	s_add_i32 s0, s8, -4
	s_min_u32 s0, s0, 0x79
	s_add_i32 s0, s0, s4
	v_mov_b32_e32 v94, v7
	v_mov_b32_e32 v96, v6
	v_mov_b64_e32 v[92:93], v[56:57]
	s_lshl_b32 s0, s0, 2
	v_mov_b32_e32 v97, v9
	v_mov_b32_e32 v95, v8
	v_mov_b64_e32 v[90:91], v[54:55]
	v_lshlrev_b32_e32 v54, 16, v96
	v_and_b32_e32 v55, 0xffff0000, v96
	v_lshlrev_b32_e32 v56, 16, v94
	v_and_b32_e32 v57, 0xffff0000, v94
	s_or_b32 s0, s0, s3
	v_lshlrev_b32_e32 v94, 16, v95
	v_and_b32_e32 v95, 0xffff0000, v95
	v_lshlrev_b32_e32 v96, 16, v97
	v_and_b32_e32 v97, 0xffff0000, v97
	v_pk_fma_f32 v[98:99], v[64:65], v[48:49], v[56:57]
	v_pk_fma_f32 v[100:101], v[62:63], v[46:47], v[54:55]
	v_cvt_pk_bf16_f32 v46, v46, v47
	v_cvt_pk_bf16_f32 v47, v48, v49
	v_cvt_pk_bf16_f32 v48, v78, v79
	v_cvt_pk_bf16_f32 v49, v80, v81
	v_lshl_add_u64 v[54:55], v[82:83], 0, s[10:11]
	s_lshl_b64 s[10:11], s[0:1], 16
	global_load_dwordx4 v[6:9], v[2:3], off nt
	s_nop 0
	global_load_dwordx4 v[2:5], v[10:11], off nt
	s_nop 0
	global_load_dwordx4 v[10:13], v[10:11], off offset:64 nt
	v_pk_fma_f32 v[96:97], v[68:69], v[80:81], v[96:97]
	v_pk_fma_f32 v[94:95], v[66:67], v[78:79], v[94:95]
	v_lshlrev_b32_e32 v78, 16, v102
	global_store_dwordx4 v[54:55], v[46:49], off
	v_and_b32_e32 v79, 0xffff0000, v102
	v_lshlrev_b32_e32 v80, 16, v1
	v_lshl_add_u64 v[46:47], v[82:83], 0, s[10:11]
	s_lshl_b64 s[10:11], s[0:1], 9
	v_lshl_add_u64 v[48:49], v[84:85], 0, s[10:11]
	global_load_dwordx4 v[66:69], v[46:47], off nt
	global_load_dwordx4 v[54:57], v[48:49], off nt
	global_load_dwordx4 v[62:65], v[48:49], off offset:64 nt
	v_lshlrev_b32_e32 v46, 16, v104
	v_and_b32_e32 v47, 0xffff0000, v104
	v_lshlrev_b32_e32 v48, 16, v103
	v_and_b32_e32 v49, 0xffff0000, v103
	v_and_b32_e32 v81, 0xffff0000, v1
	v_pk_fma_f32 v[48:49], v[92:93], v[98:99], v[48:49]
	v_pk_fma_f32 v[46:47], v[90:91], v[100:101], v[46:47]
	v_pk_fma_f32 v[80:81], v[88:89], v[96:97], v[80:81]
	v_pk_fma_f32 v[78:79], v[86:87], v[94:95], v[78:79]
	s_add_i32 s0, s6, -16
	s_lshl_b64 s[10:11], s[0:1], 16
	v_cvt_pk_bf16_f32 v86, v100, v101
	v_cvt_pk_bf16_f32 v87, v98, v99
	v_cvt_pk_bf16_f32 v88, v94, v95
	v_cvt_pk_bf16_f32 v89, v96, v97
	v_lshl_add_u64 v[90:91], v[82:83], 0, s[10:11]
	s_cmpk_gt_u32 s9, 0x7d
	global_store_dwordx4 v[90:91], v[86:89], off
	s_cbranch_scc1 .LBB0_669
	s_add_i32 s0, s8, -3
	s_min_u32 s0, s0, 0x79
	s_add_i32 s0, s0, s4
	s_lshl_b32 s0, s0, 2
	s_or_b32 s0, s0, s3
	s_lshl_b64 s[10:11], s[0:1], 16
	v_lshl_add_u64 v[94:95], v[82:83], 0, s[10:11]
	s_lshl_b64 s[10:11], s[0:1], 9
	v_lshl_add_u64 v[90:91], v[84:85], 0, s[10:11]
	global_load_dwordx4 v[86:89], v[90:91], off nt
	s_nop 0
	global_load_dwordx4 v[90:93], v[90:91], off offset:64 nt
	s_nop 0
	global_load_dwordx4 v[94:97], v[94:95], off nt
	s_waitcnt vmcnt(22)
	v_lshlrev_b32_e32 v100, 16, v59
	v_and_b32_e32 v101, 0xffff0000, v59
	v_lshlrev_b32_e32 v98, 16, v58
	v_and_b32_e32 v99, 0xffff0000, v58
	v_lshlrev_b32_e32 v104, 16, v61
	v_and_b32_e32 v105, 0xffff0000, v61
	s_waitcnt vmcnt(21)
	v_pk_fma_f32 v[16:17], v[16:17], v[48:49], v[100:101]
	s_add_i32 s0, s6, -12
	v_lshlrev_b32_e32 v102, 16, v60
	v_and_b32_e32 v103, 0xffff0000, v60
	v_cvt_pk_bf16_f32 v58, v46, v47
	v_cvt_pk_bf16_f32 v59, v48, v49
	v_pk_fma_f32 v[14:15], v[14:15], v[46:47], v[98:99]
	s_waitcnt vmcnt(20)
	v_pk_fma_f32 v[28:29], v[28:29], v[80:81], v[104:105]
	v_mov_b64_e32 v[48:49], v[16:17]
	s_lshl_b64 s[10:11], s[0:1], 16
	v_cvt_pk_bf16_f32 v60, v78, v79
	v_cvt_pk_bf16_f32 v61, v80, v81
	v_pk_fma_f32 v[26:27], v[26:27], v[78:79], v[102:103]
	v_mov_b64_e32 v[46:47], v[14:15]
	v_mov_b64_e32 v[80:81], v[28:29]
	v_lshl_add_u64 v[14:15], v[82:83], 0, s[10:11]
	v_mov_b64_e32 v[78:79], v[26:27]
	global_store_dwordx4 v[14:15], v[58:61], off
	s_waitcnt vmcnt(3)
	v_mov_b64_e32 v[14:15], v[86:87]
	s_waitcnt vmcnt(2)
	v_mov_b64_e32 v[26:27], v[90:91]
	v_mov_b64_e32 v[16:17], v[88:89]
	v_mov_b64_e32 v[28:29], v[92:93]
	s_waitcnt vmcnt(1)
	v_mov_b32_e32 v58, v94
	v_mov_b32_e32 v59, v95
	v_mov_b32_e32 v60, v96
	v_mov_b32_e32 v61, v97
	s_cmpk_gt_u32 s9, 0x7c
	s_cbranch_scc0 .LBB0_670

; #define GAS __attribute__((address_space(1)))
; __device__ __forceinline__ unsigned pk2(float lo, float hi) { const f32x2_t v = {lo, hi}; return __builtin_bit_cast(unsigned, __builtin_convertvector(v, bf16x2_t)); }
; __device__ __forceinline__ void p3_hg_scan(int job, bf16_t* HGR, const float* dec, int tid, const bool ST = true) {
;     ...
;     for (int n0 = 0; n0 < NCH; n0 += 6) {
; #pragma unroll
;         for (int u = 0; u < 6; ++u) { const int n = n0 + u; if (n < NCH) { const int unit = (b * NCH + n) * 4 + h;
;             const v4u bv = bn[u]; const f32x4 dva = da[u], dvb = db[u];
;             const int nn = (n + 6 < NCH) ? n + 6 : NCH - 1; const int unit2 = (b * NCH + nn) * 4 + h;
;             bn[u] = *(const GAS v4u*)(HGR + (size_t)unit2 * 32768 + eoff); da[u] = *(const GAS f32x4*)(dec + (size_t)unit2 * 128 + koff); db[u] = *(const GAS f32x4*)(dec + (size_t)unit2 * 128 + koff + 16);
;             f32x4 b0, b1; unpack8(bv, b0, b1);
;             const f32x4 Sn0 = S0 * dva + b0, Sn1 = S1 * dvb + b1;
;             asm volatile("" :: "v"(Sn0[0]), "v"(Sn0[1]), "v"(Sn0[2]), "v"(Sn0[3]), "v"(Sn1[0]), "v"(Sn1[1]), "v"(Sn1[2]), "v"(Sn1[3]) : "memory");
;             if (ST) *(GAS v4u*)(HGR + (size_t)unit * 32768 + eoff) = (v4u){pk2(S0[0], S0[1]), pk2(S0[2], S0[3]), pk2(S1[0], S1[1]), pk2(S1[2], S1[3])};
;             S0 = Sn0; S1 = Sn1; } }
.LBB0_668:
	s_add_i32 s0, s8, -1
	s_min_u32 s0, s0, 0x79
	s_add_i32 s0, s0, s4
	s_lshl_b32 s0, s0, 2
	s_or_b32 s0, s0, s3
	s_lshl_b64 s[10:11], s[0:1], 16
	v_lshl_add_u64 v[94:95], v[82:83], 0, s[10:11]
	s_lshl_b64 s[10:11], s[0:1], 9
	v_lshl_add_u64 v[90:91], v[84:85], 0, s[10:11]
	global_load_dwordx4 v[86:89], v[90:91], off nt
	s_nop 0
	global_load_dwordx4 v[90:93], v[90:91], off offset:64 nt
	s_nop 0
	global_load_dwordx4 v[94:97], v[94:95], off nt
	s_waitcnt vmcnt(16)
	v_lshlrev_b32_e32 v100, 16, v71
	v_and_b32_e32 v101, 0xffff0000, v71
	v_lshlrev_b32_e32 v98, 16, v70
	v_and_b32_e32 v99, 0xffff0000, v70
	v_lshlrev_b32_e32 v104, 16, v73
	v_and_b32_e32 v105, 0xffff0000, v73
	s_waitcnt vmcnt(15)
	v_pk_fma_f32 v[32:33], v[32:33], v[48:49], v[100:101]
	s_add_i32 s0, s6, -4
	v_lshlrev_b32_e32 v102, 16, v72
	v_and_b32_e32 v103, 0xffff0000, v72
	v_cvt_pk_bf16_f32 v70, v46, v47
	v_cvt_pk_bf16_f32 v71, v48, v49
	v_pk_fma_f32 v[30:31], v[30:31], v[46:47], v[98:99]
	s_waitcnt vmcnt(14)
	v_pk_fma_f32 v[44:45], v[44:45], v[80:81], v[104:105]
	v_mov_b64_e32 v[48:49], v[32:33]
	s_lshl_b64 s[10:11], s[0:1], 16
	v_cvt_pk_bf16_f32 v72, v78, v79
	v_cvt_pk_bf16_f32 v73, v80, v81
	v_pk_fma_f32 v[42:43], v[42:43], v[78:79], v[102:103]
	v_mov_b64_e32 v[46:47], v[30:31]
	v_mov_b64_e32 v[80:81], v[44:45]
	v_lshl_add_u64 v[30:31], v[82:83], 0, s[10:11]
	v_mov_b64_e32 v[78:79], v[42:43]
	global_store_dwordx4 v[30:31], v[70:73], off
	s_waitcnt vmcnt(3)
	v_mov_b64_e32 v[30:31], v[86:87]
	s_waitcnt vmcnt(2)
	v_mov_b64_e32 v[42:43], v[90:91]
	v_mov_b64_e32 v[32:33], v[88:89]
	v_mov_b64_e32 v[44:45], v[92:93]
	s_waitcnt vmcnt(1)
	v_mov_b32_e32 v70, v94
	v_mov_b32_e32 v71, v95
	v_mov_b32_e32 v72, v96
	v_mov_b32_e32 v73, v97
	s_cmpk_gt_u32 s9, 0x7a
	s_cbranch_scc1 .LBB0_664
	s_branch .LBB0_672

; #define GAS __attribute__((address_space(1)))
; __device__ __forceinline__ unsigned pk2(float lo, float hi) { const f32x2_t v = {lo, hi}; return __builtin_bit_cast(unsigned, __builtin_convertvector(v, bf16x2_t)); }
; __device__ __forceinline__ void p3_hg_scan(int job, bf16_t* HGR, const float* dec, int tid, const bool ST = true) {
;     ...
;     for (int n0 = 0; n0 < NCH; n0 += 6) {
; #pragma unroll
;         for (int u = 0; u < 6; ++u) { const int n = n0 + u; if (n < NCH) { const int unit = (b * NCH + n) * 4 + h;
;             const v4u bv = bn[u]; const f32x4 dva = da[u], dvb = db[u];
;             const int nn = (n + 6 < NCH) ? n + 6 : NCH - 1; const int unit2 = (b * NCH + nn) * 4 + h;
;             bn[u] = *(const GAS v4u*)(HGR + (size_t)unit2 * 32768 + eoff); da[u] = *(const GAS f32x4*)(dec + (size_t)unit2 * 128 + koff); db[u] = *(const GAS f32x4*)(dec + (size_t)unit2 * 128 + koff + 16);
;             f32x4 b0, b1; unpack8(bv, b0, b1);
;             const f32x4 Sn0 = S0 * dva + b0, Sn1 = S1 * dvb + b1;
;             asm volatile("" :: "v"(Sn0[0]), "v"(Sn0[1]), "v"(Sn0[2]), "v"(Sn0[3]), "v"(Sn1[0]), "v"(Sn1[1]), "v"(Sn1[2]), "v"(Sn1[3]) : "memory");
;             if (ST) *(GAS v4u*)(HGR + (size_t)unit * 32768 + eoff) = (v4u){pk2(S0[0], S0[1]), pk2(S0[2], S0[3]), pk2(S1[0], S1[1]), pk2(S1[2], S1[3])};
;             S0 = Sn0; S1 = Sn1; } }
.LBB0_670:
	s_add_i32 s0, s8, -2
	s_min_u32 s0, s0, 0x79
	s_add_i32 s0, s0, s4
	s_lshl_b32 s0, s0, 2
	s_or_b32 s0, s0, s3
	s_lshl_b64 s[10:11], s[0:1], 16
	v_lshl_add_u64 v[94:95], v[82:83], 0, s[10:11]
	s_lshl_b64 s[10:11], s[0:1], 9
	v_lshl_add_u64 v[90:91], v[84:85], 0, s[10:11]
	global_load_dwordx4 v[86:89], v[90:91], off nt
	s_nop 0
	global_load_dwordx4 v[90:93], v[90:91], off offset:64 nt
	s_nop 0
	global_load_dwordx4 v[94:97], v[94:95], off nt
	s_waitcnt vmcnt(19)
	v_lshlrev_b32_e32 v100, 16, v51
	v_and_b32_e32 v101, 0xffff0000, v51
	v_lshlrev_b32_e32 v98, 16, v50
	v_and_b32_e32 v99, 0xffff0000, v50
	v_lshlrev_b32_e32 v104, 16, v53
	v_and_b32_e32 v105, 0xffff0000, v53
	s_waitcnt vmcnt(18)
	v_pk_fma_f32 v[20:21], v[20:21], v[48:49], v[100:101]
	s_add_i32 s0, s6, -8
	v_lshlrev_b32_e32 v102, 16, v52
	v_and_b32_e32 v103, 0xffff0000, v52
	v_cvt_pk_bf16_f32 v50, v46, v47
	v_cvt_pk_bf16_f32 v51, v48, v49
	v_pk_fma_f32 v[18:19], v[18:19], v[46:47], v[98:99]
	s_waitcnt vmcnt(17)
	v_pk_fma_f32 v[24:25], v[24:25], v[80:81], v[104:105]
	v_mov_b64_e32 v[48:49], v[20:21]
	s_lshl_b64 s[10:11], s[0:1], 16
	v_cvt_pk_bf16_f32 v52, v78, v79
	v_cvt_pk_bf16_f32 v53, v80, v81
	v_pk_fma_f32 v[22:23], v[22:23], v[78:79], v[102:103]
	v_mov_b64_e32 v[46:47], v[18:19]
	v_mov_b64_e32 v[80:81], v[24:25]
	v_lshl_add_u64 v[18:19], v[82:83], 0, s[10:11]
	v_mov_b64_e32 v[78:79], v[22:23]
	global_store_dwordx4 v[18:19], v[50:53], off
	s_waitcnt vmcnt(3)
	v_mov_b64_e32 v[18:19], v[86:87]
	s_waitcnt vmcnt(2)
	v_mov_b64_e32 v[22:23], v[90:91]
	v_mov_b64_e32 v[20:21], v[88:89]
	v_mov_b64_e32 v[24:25], v[92:93]
	s_waitcnt vmcnt(1)
	v_mov_b32_e32 v50, v94
	v_mov_b32_e32 v51, v95
	v_mov_b32_e32 v52, v96
	v_mov_b32_e32 v53, v97
	s_cmpk_gt_u32 s9, 0x7b
	s_cbranch_scc0 .LBB0_668

; #define GAS __attribute__((address_space(1)))
; __device__ __forceinline__ unsigned pk2(float lo, float hi) { const f32x2_t v = {lo, hi}; return __builtin_bit_cast(unsigned, __builtin_convertvector(v, bf16x2_t)); }
; __device__ __forceinline__ void p3_hg_scan(int job, bf16_t* HGR, const float* dec, int tid, const bool ST = true) {
;     ...
;     for (int n0 = 0; n0 < NCH; n0 += 6) {
; #pragma unroll
;         for (int u = 0; u < 6; ++u) { const int n = n0 + u; if (n < NCH) { const int unit = (b * NCH + n) * 4 + h;
;             const v4u bv = bn[u]; const f32x4 dva = da[u], dvb = db[u];
;             const int nn = (n + 6 < NCH) ? n + 6 : NCH - 1; const int unit2 = (b * NCH + nn) * 4 + h;
;             bn[u] = *(const GAS v4u*)(HGR + (size_t)unit2 * 32768 + eoff); da[u] = *(const GAS f32x4*)(dec + (size_t)unit2 * 128 + koff); db[u] = *(const GAS f32x4*)(dec + (size_t)unit2 * 128 + koff + 16);
;             f32x4 b0, b1; unpack8(bv, b0, b1);
;             const f32x4 Sn0 = S0 * dva + b0, Sn1 = S1 * dvb + b1;
;             asm volatile("" :: "v"(Sn0[0]), "v"(Sn0[1]), "v"(Sn0[2]), "v"(Sn0[3]), "v"(Sn1[0]), "v"(Sn1[1]), "v"(Sn1[2]), "v"(Sn1[3]) : "memory");
;             if (ST) *(GAS v4u*)(HGR + (size_t)unit * 32768 + eoff) = (v4u){pk2(S0[0], S0[1]), pk2(S0[2], S0[3]), pk2(S1[0], S1[1]), pk2(S1[2], S1[3])};
;             S0 = Sn0; S1 = Sn1; } }
.LBB0_672:
	s_min_u32 s0, s8, 0x79
	s_add_i32 s0, s0, s4
	s_lshl_b32 s0, s0, 2
	s_or_b32 s0, s0, s3
	s_lshl_b64 s[10:11], s[0:1], 16
	v_lshl_add_u64 v[94:95], v[82:83], 0, s[10:11]
	s_lshl_b64 s[10:11], s[0:1], 9
	v_lshl_add_u64 v[90:91], v[84:85], 0, s[10:11]
	global_load_dwordx4 v[86:89], v[90:91], off nt
	s_nop 0
	global_load_dwordx4 v[90:93], v[90:91], off offset:64 nt
	s_nop 0
	global_load_dwordx4 v[94:97], v[94:95], off nt
	s_waitcnt vmcnt(13)
	v_lshlrev_b32_e32 v100, 16, v75
	v_and_b32_e32 v101, 0xffff0000, v75
	v_lshlrev_b32_e32 v104, 16, v77
	v_and_b32_e32 v105, 0xffff0000, v77
	v_lshlrev_b32_e32 v98, 16, v74
	v_and_b32_e32 v99, 0xffff0000, v74
	v_lshlrev_b32_e32 v102, 16, v76
	v_and_b32_e32 v103, 0xffff0000, v76
	s_mov_b32 s7, s1
	s_waitcnt vmcnt(12)
	v_pk_fma_f32 v[36:37], v[36:37], v[48:49], v[100:101]
	s_waitcnt vmcnt(11)
	v_pk_fma_f32 v[40:41], v[40:41], v[80:81], v[104:105]
	v_cvt_pk_bf16_f32 v74, v46, v47
	v_cvt_pk_bf16_f32 v75, v48, v49
	v_cvt_pk_bf16_f32 v76, v78, v79
	v_cvt_pk_bf16_f32 v77, v80, v81
	v_pk_fma_f32 v[34:35], v[34:35], v[46:47], v[98:99]
	v_pk_fma_f32 v[38:39], v[38:39], v[78:79], v[102:103]
	s_lshl_b64 s[10:11], s[6:7], 16
	v_mov_b64_e32 v[80:81], v[40:41]
	v_mov_b64_e32 v[48:49], v[36:37]
	v_lshl_add_u64 v[98:99], v[82:83], 0, s[10:11]
	v_mov_b64_e32 v[78:79], v[38:39]
	v_mov_b64_e32 v[46:47], v[34:35]
	global_store_dwordx4 v[98:99], v[74:77], off
	s_waitcnt vmcnt(3)
	v_mov_b64_e32 v[34:35], v[86:87]
	s_waitcnt vmcnt(2)
	v_mov_b64_e32 v[38:39], v[90:91]
	v_mov_b64_e32 v[36:37], v[88:89]
	v_mov_b64_e32 v[40:41], v[92:93]
	s_waitcnt vmcnt(1)
	v_mov_b32_e32 v74, v94
	v_mov_b32_e32 v75, v95
	v_mov_b32_e32 v76, v96
	v_mov_b32_e32 v77, v97
	s_branch .LBB0_664

; #define GAS __attribute__((address_space(1)))
; #define LAS __attribute__((address_space(3)))
; #define LDS_WAIT() asm volatile("s_waitcnt lgkmcnt(0)" ::: "memory")
; __device__ __forceinline__ void p0_transpose_item(const float* W, int ldw, int src_col0, int k0, bf16_t* WT, int ldk, int dst_row0, int dst_k0, LAS float* scr, int lane) {
; #pragma unroll
;     for (int i = 0; i < 8; ++i) { const int kk = 8 * i + (lane >> 3), n4 = 4 * (lane & 7);
;         const f32x4 w = *(const GAS f32x4*)(W + (size_t)(k0 + kk) * ldw + src_col0 + n4); LAS float* d = scr + kk * 33 + n4; d[0] = w[0]; d[1] = w[1]; d[2] = w[2]; d[3] = w[3]; }
;     LDS_WAIT(); asm volatile("" ::: "memory");
;     const int c = lane & 7;
; #pragma unroll
;     for (int j = 0; j < 4; ++j) { const int n = (lane >> 3) + 8 * j; const LAS float* s = scr + (8 * c) * 33 + n;
;         v4u o; o.x = pk2(s[0 * 33], s[1 * 33]); o.y = pk2(s[2 * 33], s[3 * 33]); o.z = pk2(s[4 * 33], s[5 * 33]); o.w = pk2(s[6 * 33], s[7 * 33]);
;         *(GAS v4u*)(WT + (size_t)(dst_row0 + n) * ldk + dst_k0 + k0 + 8 * c) = o; }
;     LDS_WAIT(); asm volatile("" ::: "memory");
; __global__ void __launch_bounds__(NWAVES * 64, 2) fwd(Args args) {
;     ...
;                 if (blockIdx.x < 64) for (int it = ((int)blockIdx.x - 32) * NWAVES + wave; it < I_BA + I_BB + I_O + I_UP + I_DN; it += 32 * NWAVES) {
;                     int r = it;
;                     if (r < I_BA) { const int kb = r / 32, nb = r % 32; p0_transpose_item(wba, 1024, 32 * nb, 64 * kb, WBAB_T, 1024, 32 * nb, 0, scr, lane); continue; } r -= I_BA;
;                     if (r < I_BB) { const int kb = r / 32, nb = r % 32; p0_transpose_item(wbb, 1024, 32 * nb, 64 * kb, WBAB_T, 1024, 32 * nb, 512, scr, lane); continue; } r -= I_BB;
;                     if (r < I_O) { const int kb = r / 32, nb = r % 32; p0_transpose_item(wo, 1024, 32 * nb, 64 * kb, WO_T, 1024, 32 * nb, 0, scr, lane); continue; } r -= I_O;
;                     if (r < I_UP) { const int kb = r / 128, nb = r % 128; p0_transpose_item(wup, FF, 32 * nb, 64 * kb, WUP_T, 1024, 32 * nb, 0, scr, lane); continue; } r -= I_UP;
;                     { const int kb = r / 32, nb = r % 32; p0_transpose_item(wdn, 1024, 32 * nb, 64 * kb, WDN_T, FF, 32 * nb, 0, scr, lane); }
.LBB0_822:
	s_cmpk_gt_i32 s4, 0xff
	s_mov_b64 s[6:7], -1
	s_cbranch_scc0 .LBB0_836
	s_cmpk_gt_u32 s4, 0x1ff
	s_cbranch_scc0 .LBB0_833
	s_cmpk_gt_u32 s4, 0x3ff
	s_cbranch_scc0 .LBB0_830
	s_cmpk_gt_u32 s4, 0xbff
	s_cbranch_scc0 .LBB0_827
	s_and_b32 s0, s8, 0x7fffffc0
	s_add_i32 s6, s0, 0xffffe800
	v_or_b32_e32 v2, s6, v1
	v_lshlrev_b64 v[48:49], 12, v[2:3]
	v_or_b32_e32 v2, s6, v24
	v_lshlrev_b64 v[50:51], 12, v[2:3]
	v_or_b32_e32 v2, s6, v25
	v_lshlrev_b64 v[56:57], 12, v[2:3]
	v_or_b32_e32 v2, s6, v26
	s_and_b32 s3, s5, 0x3e0
	v_lshlrev_b64 v[58:59], 12, v[2:3]
	v_or_b32_e32 v2, s6, v27
	s_lshl_b32 s0, s3, 2
	v_lshlrev_b64 v[64:65], 12, v[2:3]
	v_or_b32_e32 v2, s6, v28
	v_lshl_add_u64 v[76:77], v[4:5], 0, s[0:1]
	v_lshlrev_b64 v[66:67], 12, v[2:3]
	v_lshl_add_u64 v[48:49], v[76:77], 0, v[48:49]
	v_lshl_add_u64 v[52:53], v[76:77], 0, v[50:51]
	v_lshl_add_u64 v[56:57], v[76:77], 0, v[56:57]
	v_lshl_add_u64 v[60:61], v[76:77], 0, v[58:59]
	v_lshl_add_u64 v[64:65], v[76:77], 0, v[64:65]
	v_lshl_add_u64 v[68:69], v[76:77], 0, v[66:67]
	global_load_dwordx4 v[48:51], v[48:49], off nt
	s_nop 0
	global_load_dwordx4 v[52:55], v[52:53], off nt
	s_nop 0
	global_load_dwordx4 v[56:59], v[56:57], off nt
	s_nop 0
	global_load_dwordx4 v[60:63], v[60:61], off nt
	s_nop 0
	global_load_dwordx4 v[64:67], v[64:65], off nt
	s_nop 0
	global_load_dwordx4 v[68:71], v[68:69], off nt
	v_or_b32_e32 v2, s6, v29
	v_lshlrev_b64 v[72:73], 12, v[2:3]
	v_lshl_add_u64 v[72:73], v[76:77], 0, v[72:73]
	v_or_b32_e32 v2, s6, v30
	global_load_dwordx4 v[72:75], v[72:73], off nt
	v_lshlrev_b64 v[78:79], 12, v[2:3]
	v_lshl_add_u64 v[76:77], v[76:77], 0, v[78:79]
	global_load_dwordx4 v[76:79], v[76:77], off nt
	s_mov_b32 s7, s1
	v_or_b32_e32 v2, s3, v1
	v_or_b32_e32 v47, s3, v24
	v_lshl_add_u64 v[80:81], s[6:7], 1, v[6:7]
	v_lshlrev_b32_e32 v2, 13, v2
	v_or_b32_e32 v86, s3, v25
	v_lshl_add_u64 v[82:83], v[80:81], 0, v[2:3]
	v_lshlrev_b32_e32 v2, 13, v47
	v_or_b32_e32 v92, s3, v26
	v_lshl_add_u64 v[84:85], v[80:81], 0, v[2:3]
	v_lshlrev_b32_e32 v2, 13, v86
	v_lshl_add_u64 v[86:87], v[80:81], 0, v[2:3]
	v_lshlrev_b32_e32 v2, 13, v92
	s_mov_b64 s[6:7], 0
	s_waitcnt vmcnt(7)
	ds_write2_b32 v32, v48, v49 offset1:1
	ds_write2_b32 v32, v50, v51 offset0:2 offset1:3
	s_waitcnt vmcnt(6)
	ds_write2_b32 v33, v52, v53 offset1:1
	ds_write2_b32 v34, v54, v55 offset1:1
	s_waitcnt vmcnt(5)
	ds_write2_b32 v35, v56, v57 offset1:1
	ds_write2_b32 v36, v58, v59 offset1:1
	s_waitcnt vmcnt(4)
	ds_write2_b32 v37, v60, v61 offset1:1
	ds_write2_b32 v38, v62, v63 offset1:1
	s_waitcnt vmcnt(3)
	ds_write2_b32 v39, v64, v65 offset1:1
	ds_write2_b32 v40, v66, v67 offset1:1
	s_waitcnt vmcnt(2)
	ds_write2_b32 v41, v68, v69 offset1:1
	ds_write2_b32 v42, v70, v71 offset1:1
	s_waitcnt vmcnt(1)
	ds_write2_b32 v43, v72, v73 offset1:1
	ds_write2_b32 v44, v74, v75 offset1:1
	s_waitcnt vmcnt(0)
	ds_write2_b32 v45, v76, v77 offset1:1
	ds_write2_b32 v46, v78, v79 offset1:1
	s_waitcnt lgkmcnt(0)
	ds_read2_b32 v[52:53], v31 offset0:33 offset1:41
	ds_read2_b32 v[54:55], v31 offset1:8
	ds_read2_b32 v[56:57], v31 offset0:66 offset1:74
	ds_read2_b32 v[58:59], v31 offset0:99 offset1:107
	ds_read2_b32 v[60:61], v31 offset0:132 offset1:140
	ds_read2_b32 v[62:63], v31 offset0:165 offset1:173
	ds_read2_b32 v[64:65], v31 offset0:198 offset1:206
	ds_read2_b32 v[66:67], v31 offset0:231 offset1:239
	ds_read2_b32 v[68:69], v31 offset0:49 offset1:57
	ds_read2_b32 v[70:71], v31 offset0:16 offset1:24
	ds_read2_b32 v[72:73], v31 offset0:82 offset1:90
	ds_read2_b32 v[74:75], v31 offset0:115 offset1:123
	ds_read2_b32 v[76:77], v31 offset0:148 offset1:156
	ds_read2_b32 v[78:79], v31 offset0:181 offset1:189
	ds_read2_b32 v[88:89], v31 offset0:214 offset1:222
	ds_read2_b32 v[90:91], v31 offset0:247 offset1:255
	s_waitcnt lgkmcnt(14)
	v_cvt_pk_bf16_f32 v48, v54, v52
	s_waitcnt lgkmcnt(12)
	v_cvt_pk_bf16_f32 v49, v56, v58
	s_waitcnt lgkmcnt(10)
	v_cvt_pk_bf16_f32 v50, v60, v62
	s_waitcnt lgkmcnt(8)
	v_cvt_pk_bf16_f32 v51, v64, v66
	v_cvt_pk_bf16_f32 v52, v55, v53
	v_cvt_pk_bf16_f32 v53, v57, v59
	v_cvt_pk_bf16_f32 v54, v61, v63
	v_cvt_pk_bf16_f32 v55, v65, v67
	s_waitcnt lgkmcnt(6)
	v_cvt_pk_bf16_f32 v56, v70, v68
	s_waitcnt lgkmcnt(4)
	v_cvt_pk_bf16_f32 v57, v72, v74
	s_waitcnt lgkmcnt(2)
	v_cvt_pk_bf16_f32 v58, v76, v78
	s_waitcnt lgkmcnt(0)
	v_cvt_pk_bf16_f32 v59, v88, v90
	v_cvt_pk_bf16_f32 v60, v71, v69
	v_cvt_pk_bf16_f32 v61, v73, v75
	v_cvt_pk_bf16_f32 v62, v77, v79
	v_cvt_pk_bf16_f32 v63, v89, v91
	global_store_dwordx4 v[82:83], v[48:51], off
	global_store_dwordx4 v[84:85], v[52:55], off
	global_store_dwordx4 v[86:87], v[56:59], off
	v_lshl_add_u64 v[48:49], v[80:81], 0, v[2:3]
	global_store_dwordx4 v[48:49], v[60:63], off
	s_waitcnt lgkmcnt(0)
; #define GAS __attribute__((address_space(1)))
; #define LAS __attribute__((address_space(3)))
; #define LDS_WAIT() asm volatile("s_waitcnt lgkmcnt(0)" ::: "memory")
; __device__ __forceinline__ unsigned pk2(float lo, float hi) { const f32x2_t v = {lo, hi}; return __builtin_bit_cast(unsigned, __builtin_convertvector(v, bf16x2_t)); }
; __device__ __forceinline__ void p0_transpose_item(const float* W, int ldw, int src_col0, int k0, bf16_t* WT, int ldk, int dst_row0, int dst_k0, LAS float* scr, int lane) {
; #pragma unroll
;     for (int i = 0; i < 8; ++i) { const int kk = 8 * i + (lane >> 3), n4 = 4 * (lane & 7);
;         const f32x4 w = *(const GAS f32x4*)(W + (size_t)(k0 + kk) * ldw + src_col0 + n4); LAS float* d = scr + kk * 33 + n4; d[0] = w[0]; d[1] = w[1]; d[2] = w[2]; d[3] = w[3]; }
;     LDS_WAIT(); asm volatile("" ::: "memory");
;     const int c = lane & 7;
; #pragma unroll
;     for (int j = 0; j < 4; ++j) { const int n = (lane >> 3) + 8 * j; const LAS float* s = scr + (8 * c) * 33 + n;
;         v4u o; o.x = pk2(s[0 * 33], s[1 * 33]); o.y = pk2(s[2 * 33], s[3 * 33]); o.z = pk2(s[4 * 33], s[5 * 33]); o.w = pk2(s[6 * 33], s[7 * 33]);
;         *(GAS v4u*)(WT + (size_t)(dst_row0 + n) * ldk + dst_k0 + k0 + 8 * c) = o; }
;     LDS_WAIT(); asm volatile("" ::: "memory");
; __global__ void __launch_bounds__(NWAVES * 64, 2) fwd(Args args) {
;     ...
;                 if (blockIdx.x < 64) for (int it = ((int)blockIdx.x - 32) * NWAVES + wave; it < I_BA + I_BB + I_O + I_UP + I_DN; it += 32 * NWAVES) {
;                     int r = it;
;                     if (r < I_BA) { const int kb = r / 32, nb = r % 32; p0_transpose_item(wba, 1024, 32 * nb, 64 * kb, WBAB_T, 1024, 32 * nb, 0, scr, lane); continue; } r -= I_BA;
;                     if (r < I_BB) { const int kb = r / 32, nb = r % 32; p0_transpose_item(wbb, 1024, 32 * nb, 64 * kb, WBAB_T, 1024, 32 * nb, 512, scr, lane); continue; } r -= I_BB;
;                     if (r < I_O) { const int kb = r / 32, nb = r % 32; p0_transpose_item(wo, 1024, 32 * nb, 64 * kb, WO_T, 1024, 32 * nb, 0, scr, lane); continue; } r -= I_O;
;                     if (r < I_UP) { const int kb = r / 128, nb = r % 128; p0_transpose_item(wup, FF, 32 * nb, 64 * kb, WUP_T, 1024, 32 * nb, 0, scr, lane); continue; } r -= I_UP;
.LBB0_827:
	s_andn2_b64 vcc, exec, s[6:7]
	s_cbranch_vccnz .LBB0_829
	s_add_i32 s0, s4, 0xfffffc00
	s_lshr_b32 s0, s0, 1
	s_and_b32 s6, s0, 0x7fffffc0
	v_or_b32_e32 v2, s6, v1
	v_lshlrev_b64 v[48:49], 14, v[2:3]
	v_or_b32_e32 v2, s6, v24
	v_lshlrev_b64 v[50:51], 14, v[2:3]
	v_or_b32_e32 v2, s6, v25
	v_lshlrev_b64 v[56:57], 14, v[2:3]
	v_or_b32_e32 v2, s6, v26
	s_and_b32 s3, s5, 0xfe0
	v_lshlrev_b64 v[58:59], 14, v[2:3]
	v_or_b32_e32 v2, s6, v27
	s_lshl_b32 s0, s3, 2
	v_lshlrev_b64 v[64:65], 14, v[2:3]
	v_or_b32_e32 v2, s6, v28
	v_lshl_add_u64 v[76:77], v[8:9], 0, s[0:1]
	v_lshlrev_b64 v[66:67], 14, v[2:3]
	v_lshl_add_u64 v[48:49], v[76:77], 0, v[48:49]
	v_lshl_add_u64 v[52:53], v[76:77], 0, v[50:51]
	v_lshl_add_u64 v[56:57], v[76:77], 0, v[56:57]
	v_lshl_add_u64 v[60:61], v[76:77], 0, v[58:59]
	v_lshl_add_u64 v[64:65], v[76:77], 0, v[64:65]
	v_lshl_add_u64 v[68:69], v[76:77], 0, v[66:67]
	global_load_dwordx4 v[48:51], v[48:49], off nt
	s_nop 0
	global_load_dwordx4 v[52:55], v[52:53], off nt
	s_nop 0
	global_load_dwordx4 v[56:59], v[56:57], off nt
	s_nop 0
	global_load_dwordx4 v[60:63], v[60:61], off nt
	s_nop 0
	global_load_dwordx4 v[64:67], v[64:65], off nt
	s_nop 0
	global_load_dwordx4 v[68:71], v[68:69], off nt
	v_or_b32_e32 v2, s6, v29
	v_lshlrev_b64 v[72:73], 14, v[2:3]
	v_lshl_add_u64 v[72:73], v[76:77], 0, v[72:73]
	v_or_b32_e32 v2, s6, v30
	global_load_dwordx4 v[72:75], v[72:73], off nt
	v_lshlrev_b64 v[78:79], 14, v[2:3]
	v_lshl_add_u64 v[76:77], v[76:77], 0, v[78:79]
	global_load_dwordx4 v[76:79], v[76:77], off nt
	v_or_b32_e32 v2, s3, v1
	s_lshl_b32 s0, s6, 1
	v_or_b32_e32 v47, s3, v24
	v_lshl_add_u64 v[80:81], v[10:11], 0, s[0:1]
	v_lshlrev_b32_e32 v2, 11, v2
	v_or_b32_e32 v86, s3, v25
	v_lshl_add_u64 v[82:83], v[80:81], 0, v[2:3]
	v_lshlrev_b32_e32 v2, 11, v47
	v_or_b32_e32 v92, s3, v26
	v_lshl_add_u64 v[84:85], v[80:81], 0, v[2:3]
	v_lshlrev_b32_e32 v2, 11, v86
	v_lshl_add_u64 v[86:87], v[80:81], 0, v[2:3]
	v_lshlrev_b32_e32 v2, 11, v92
	s_waitcnt vmcnt(7)
	ds_write2_b32 v32, v48, v49 offset1:1
	ds_write2_b32 v32, v50, v51 offset0:2 offset1:3
	s_waitcnt vmcnt(6)
	ds_write2_b32 v33, v52, v53 offset1:1
	ds_write2_b32 v34, v54, v55 offset1:1
	s_waitcnt vmcnt(5)
	ds_write2_b32 v35, v56, v57 offset1:1
	ds_write2_b32 v36, v58, v59 offset1:1
	s_waitcnt vmcnt(4)
	ds_write2_b32 v37, v60, v61 offset1:1
	ds_write2_b32 v38, v62, v63 offset1:1
	s_waitcnt vmcnt(3)
	ds_write2_b32 v39, v64, v65 offset1:1
	ds_write2_b32 v40, v66, v67 offset1:1
	s_waitcnt vmcnt(2)
	ds_write2_b32 v41, v68, v69 offset1:1
	ds_write2_b32 v42, v70, v71 offset1:1
	s_waitcnt vmcnt(1)
	ds_write2_b32 v43, v72, v73 offset1:1
	ds_write2_b32 v44, v74, v75 offset1:1
	s_waitcnt vmcnt(0)
	ds_write2_b32 v45, v76, v77 offset1:1
	ds_write2_b32 v46, v78, v79 offset1:1
	s_waitcnt lgkmcnt(0)
	ds_read2_b32 v[52:53], v31 offset0:33 offset1:41
	ds_read2_b32 v[54:55], v31 offset1:8
	ds_read2_b32 v[56:57], v31 offset0:66 offset1:74
	ds_read2_b32 v[58:59], v31 offset0:99 offset1:107
	ds_read2_b32 v[60:61], v31 offset0:132 offset1:140
	ds_read2_b32 v[62:63], v31 offset0:165 offset1:173
	ds_read2_b32 v[64:65], v31 offset0:198 offset1:206
	ds_read2_b32 v[66:67], v31 offset0:231 offset1:239
	ds_read2_b32 v[68:69], v31 offset0:49 offset1:57
	ds_read2_b32 v[70:71], v31 offset0:16 offset1:24
	ds_read2_b32 v[72:73], v31 offset0:82 offset1:90
	ds_read2_b32 v[74:75], v31 offset0:115 offset1:123
	ds_read2_b32 v[76:77], v31 offset0:148 offset1:156
	ds_read2_b32 v[78:79], v31 offset0:181 offset1:189
	ds_read2_b32 v[88:89], v31 offset0:214 offset1:222
	ds_read2_b32 v[90:91], v31 offset0:247 offset1:255
	s_waitcnt lgkmcnt(14)
	v_cvt_pk_bf16_f32 v48, v54, v52
	s_waitcnt lgkmcnt(12)
	v_cvt_pk_bf16_f32 v49, v56, v58
	s_waitcnt lgkmcnt(10)
	v_cvt_pk_bf16_f32 v50, v60, v62
	s_waitcnt lgkmcnt(8)
	v_cvt_pk_bf16_f32 v51, v64, v66
	v_cvt_pk_bf16_f32 v52, v55, v53
	v_cvt_pk_bf16_f32 v53, v57, v59
	v_cvt_pk_bf16_f32 v54, v61, v63
	v_cvt_pk_bf16_f32 v55, v65, v67
	s_waitcnt lgkmcnt(6)
	v_cvt_pk_bf16_f32 v56, v70, v68
	s_waitcnt lgkmcnt(4)
	v_cvt_pk_bf16_f32 v57, v72, v74
	s_waitcnt lgkmcnt(2)
	v_cvt_pk_bf16_f32 v58, v76, v78
	s_waitcnt lgkmcnt(0)
	v_cvt_pk_bf16_f32 v59, v88, v90
	v_cvt_pk_bf16_f32 v60, v71, v69
	v_cvt_pk_bf16_f32 v61, v73, v75
	v_cvt_pk_bf16_f32 v62, v77, v79
	v_cvt_pk_bf16_f32 v63, v89, v91
	global_store_dwordx4 v[82:83], v[48:51], off
	global_store_dwordx4 v[84:85], v[52:55], off
	global_store_dwordx4 v[86:87], v[56:59], off
	v_lshl_add_u64 v[48:49], v[80:81], 0, v[2:3]
	global_store_dwordx4 v[48:49], v[60:63], off
	s_waitcnt lgkmcnt(0)

; #define GAS __attribute__((address_space(1)))
; #define LAS __attribute__((address_space(3)))
; #define LDS_WAIT() asm volatile("s_waitcnt lgkmcnt(0)" ::: "memory")
; __device__ __forceinline__ unsigned pk2(float lo, float hi) { const f32x2_t v = {lo, hi}; return __builtin_bit_cast(unsigned, __builtin_convertvector(v, bf16x2_t)); }
; __device__ __forceinline__ void p0_transpose_item(const float* W, int ldw, int src_col0, int k0, bf16_t* WT, int ldk, int dst_row0, int dst_k0, LAS float* scr, int lane) {
; #pragma unroll
;     for (int i = 0; i < 8; ++i) { const int kk = 8 * i + (lane >> 3), n4 = 4 * (lane & 7);
;         const f32x4 w = *(const GAS f32x4*)(W + (size_t)(k0 + kk) * ldw + src_col0 + n4); LAS float* d = scr + kk * 33 + n4; d[0] = w[0]; d[1] = w[1]; d[2] = w[2]; d[3] = w[3]; }
;     LDS_WAIT(); asm volatile("" ::: "memory");
;     const int c = lane & 7;
; #pragma unroll
;     for (int j = 0; j < 4; ++j) { const int n = (lane >> 3) + 8 * j; const LAS float* s = scr + (8 * c) * 33 + n;
;         v4u o; o.x = pk2(s[0 * 33], s[1 * 33]); o.y = pk2(s[2 * 33], s[3 * 33]); o.z = pk2(s[4 * 33], s[5 * 33]); o.w = pk2(s[6 * 33], s[7 * 33]);
;         *(GAS v4u*)(WT + (size_t)(dst_row0 + n) * ldk + dst_k0 + k0 + 8 * c) = o; }
;     LDS_WAIT(); asm volatile("" ::: "memory");
; __global__ void __launch_bounds__(NWAVES * 64, 2) fwd(Args args) {
;     ...
;                 if (blockIdx.x < 64) for (int it = ((int)blockIdx.x - 32) * NWAVES + wave; it < I_BA + I_BB + I_O + I_UP + I_DN; it += 32 * NWAVES) {
;                     int r = it;
;                     if (r < I_BA) { const int kb = r / 32, nb = r % 32; p0_transpose_item(wba, 1024, 32 * nb, 64 * kb, WBAB_T, 1024, 32 * nb, 0, scr, lane); continue; } r -= I_BA;
;                     if (r < I_BB) { const int kb = r / 32, nb = r % 32; p0_transpose_item(wbb, 1024, 32 * nb, 64 * kb, WBAB_T, 1024, 32 * nb, 512, scr, lane); continue; } r -= I_BB;
;                     if (r < I_O) { const int kb = r / 32, nb = r % 32; p0_transpose_item(wo, 1024, 32 * nb, 64 * kb, WO_T, 1024, 32 * nb, 0, scr, lane); continue; } r -= I_O;
.LBB0_830:
	s_andn2_b64 vcc, exec, s[6:7]
	s_cbranch_vccnz .LBB0_832
	s_and_b32 s0, s8, 0x7c0
	s_add_i32 s6, s0, 0xfffffc00
	v_or_b32_e32 v2, s6, v1
	v_lshlrev_b64 v[48:49], 12, v[2:3]
	v_or_b32_e32 v2, s6, v24
	v_lshlrev_b64 v[50:51], 12, v[2:3]
	v_or_b32_e32 v2, s6, v25
	v_lshlrev_b64 v[56:57], 12, v[2:3]
	v_or_b32_e32 v2, s6, v26
	s_and_b32 s3, s5, 0x3e0
	v_lshlrev_b64 v[58:59], 12, v[2:3]
	v_or_b32_e32 v2, s6, v27
	s_lshl_b32 s0, s3, 2
	v_lshlrev_b64 v[64:65], 12, v[2:3]
	v_or_b32_e32 v2, s6, v28
	v_lshl_add_u64 v[76:77], v[12:13], 0, s[0:1]
	v_lshlrev_b64 v[66:67], 12, v[2:3]
	v_lshl_add_u64 v[48:49], v[76:77], 0, v[48:49]
	v_lshl_add_u64 v[52:53], v[76:77], 0, v[50:51]
	v_lshl_add_u64 v[56:57], v[76:77], 0, v[56:57]
	v_lshl_add_u64 v[60:61], v[76:77], 0, v[58:59]
	v_lshl_add_u64 v[64:65], v[76:77], 0, v[64:65]
	v_lshl_add_u64 v[68:69], v[76:77], 0, v[66:67]
	global_load_dwordx4 v[48:51], v[48:49], off nt
	s_nop 0
	global_load_dwordx4 v[52:55], v[52:53], off nt
	s_nop 0
	global_load_dwordx4 v[56:59], v[56:57], off nt
	s_nop 0
	global_load_dwordx4 v[60:63], v[60:61], off nt
	s_nop 0
	global_load_dwordx4 v[64:67], v[64:65], off nt
	s_nop 0
	global_load_dwordx4 v[68:71], v[68:69], off nt
	v_or_b32_e32 v2, s6, v29
	v_lshlrev_b64 v[72:73], 12, v[2:3]
	v_lshl_add_u64 v[72:73], v[76:77], 0, v[72:73]
	v_or_b32_e32 v2, s6, v30
	global_load_dwordx4 v[72:75], v[72:73], off nt
	v_lshlrev_b64 v[78:79], 12, v[2:3]
	v_lshl_add_u64 v[76:77], v[76:77], 0, v[78:79]
	global_load_dwordx4 v[76:79], v[76:77], off nt
	s_mov_b32 s7, s1
	v_or_b32_e32 v2, s3, v1
	v_or_b32_e32 v47, s3, v24
	v_lshl_add_u64 v[80:81], s[6:7], 1, v[14:15]
	v_lshlrev_b32_e32 v2, 11, v2
	v_or_b32_e32 v86, s3, v25
	v_lshl_add_u64 v[82:83], v[80:81], 0, v[2:3]
	v_lshlrev_b32_e32 v2, 11, v47
	v_or_b32_e32 v92, s3, v26
	v_lshl_add_u64 v[84:85], v[80:81], 0, v[2:3]
	v_lshlrev_b32_e32 v2, 11, v86
	v_lshl_add_u64 v[86:87], v[80:81], 0, v[2:3]
	v_lshlrev_b32_e32 v2, 11, v92
	s_waitcnt vmcnt(7)
	ds_write2_b32 v32, v48, v49 offset1:1
	ds_write2_b32 v32, v50, v51 offset0:2 offset1:3
	s_waitcnt vmcnt(6)
	ds_write2_b32 v33, v52, v53 offset1:1
	ds_write2_b32 v34, v54, v55 offset1:1
	s_waitcnt vmcnt(5)
	ds_write2_b32 v35, v56, v57 offset1:1
	ds_write2_b32 v36, v58, v59 offset1:1
	s_waitcnt vmcnt(4)
	ds_write2_b32 v37, v60, v61 offset1:1
	ds_write2_b32 v38, v62, v63 offset1:1
	s_waitcnt vmcnt(3)
	ds_write2_b32 v39, v64, v65 offset1:1
	ds_write2_b32 v40, v66, v67 offset1:1
	s_waitcnt vmcnt(2)
	ds_write2_b32 v41, v68, v69 offset1:1
	ds_write2_b32 v42, v70, v71 offset1:1
	s_waitcnt vmcnt(1)
	ds_write2_b32 v43, v72, v73 offset1:1
	ds_write2_b32 v44, v74, v75 offset1:1
	s_waitcnt vmcnt(0)
	ds_write2_b32 v45, v76, v77 offset1:1
	ds_write2_b32 v46, v78, v79 offset1:1
	s_waitcnt lgkmcnt(0)
	ds_read2_b32 v[52:53], v31 offset0:33 offset1:41
	ds_read2_b32 v[54:55], v31 offset1:8
	ds_read2_b32 v[56:57], v31 offset0:66 offset1:74
	ds_read2_b32 v[58:59], v31 offset0:99 offset1:107
	ds_read2_b32 v[60:61], v31 offset0:132 offset1:140
	ds_read2_b32 v[62:63], v31 offset0:165 offset1:173
	ds_read2_b32 v[64:65], v31 offset0:198 offset1:206
	ds_read2_b32 v[66:67], v31 offset0:231 offset1:239
	ds_read2_b32 v[68:69], v31 offset0:49 offset1:57
	ds_read2_b32 v[70:71], v31 offset0:16 offset1:24
	ds_read2_b32 v[72:73], v31 offset0:82 offset1:90
	ds_read2_b32 v[74:75], v31 offset0:115 offset1:123
	ds_read2_b32 v[76:77], v31 offset0:148 offset1:156
	ds_read2_b32 v[78:79], v31 offset0:181 offset1:189
	ds_read2_b32 v[88:89], v31 offset0:214 offset1:222
	ds_read2_b32 v[90:91], v31 offset0:247 offset1:255
	s_waitcnt lgkmcnt(14)
	v_cvt_pk_bf16_f32 v48, v54, v52
	s_waitcnt lgkmcnt(12)
	v_cvt_pk_bf16_f32 v49, v56, v58
	s_waitcnt lgkmcnt(10)
	v_cvt_pk_bf16_f32 v50, v60, v62
	s_waitcnt lgkmcnt(8)
	v_cvt_pk_bf16_f32 v51, v64, v66
	v_cvt_pk_bf16_f32 v52, v55, v53
	v_cvt_pk_bf16_f32 v53, v57, v59
	v_cvt_pk_bf16_f32 v54, v61, v63
	v_cvt_pk_bf16_f32 v55, v65, v67
	s_waitcnt lgkmcnt(6)
	v_cvt_pk_bf16_f32 v56, v70, v68
	s_waitcnt lgkmcnt(4)
	v_cvt_pk_bf16_f32 v57, v72, v74
	s_waitcnt lgkmcnt(2)
	v_cvt_pk_bf16_f32 v58, v76, v78
	s_waitcnt lgkmcnt(0)
	v_cvt_pk_bf16_f32 v59, v88, v90
	v_cvt_pk_bf16_f32 v60, v71, v69
	v_cvt_pk_bf16_f32 v61, v73, v75
	v_cvt_pk_bf16_f32 v62, v77, v79
	v_cvt_pk_bf16_f32 v63, v89, v91
	global_store_dwordx4 v[82:83], v[48:51], off
	global_store_dwordx4 v[84:85], v[52:55], off
	global_store_dwordx4 v[86:87], v[56:59], off
	v_lshl_add_u64 v[48:49], v[80:81], 0, v[2:3]
	global_store_dwordx4 v[48:49], v[60:63], off
	s_waitcnt lgkmcnt(0)

; #define GAS __attribute__((address_space(1)))
; #define LAS __attribute__((address_space(3)))
; #define LDS_WAIT() asm volatile("s_waitcnt lgkmcnt(0)" ::: "memory")
; __device__ __forceinline__ unsigned pk2(float lo, float hi) { const f32x2_t v = {lo, hi}; return __builtin_bit_cast(unsigned, __builtin_convertvector(v, bf16x2_t)); }
; __device__ __forceinline__ void p0_transpose_item(const float* W, int ldw, int src_col0, int k0, bf16_t* WT, int ldk, int dst_row0, int dst_k0, LAS float* scr, int lane) {
; #pragma unroll
;     for (int i = 0; i < 8; ++i) { const int kk = 8 * i + (lane >> 3), n4 = 4 * (lane & 7);
;         const f32x4 w = *(const GAS f32x4*)(W + (size_t)(k0 + kk) * ldw + src_col0 + n4); LAS float* d = scr + kk * 33 + n4; d[0] = w[0]; d[1] = w[1]; d[2] = w[2]; d[3] = w[3]; }
;     LDS_WAIT(); asm volatile("" ::: "memory");
;     const int c = lane & 7;
; #pragma unroll
;     for (int j = 0; j < 4; ++j) { const int n = (lane >> 3) + 8 * j; const LAS float* s = scr + (8 * c) * 33 + n;
;         v4u o; o.x = pk2(s[0 * 33], s[1 * 33]); o.y = pk2(s[2 * 33], s[3 * 33]); o.z = pk2(s[4 * 33], s[5 * 33]); o.w = pk2(s[6 * 33], s[7 * 33]);
;         *(GAS v4u*)(WT + (size_t)(dst_row0 + n) * ldk + dst_k0 + k0 + 8 * c) = o; }
;     LDS_WAIT(); asm volatile("" ::: "memory");
; __global__ void __launch_bounds__(NWAVES * 64, 2) fwd(Args args) {
;     ...
;                 if (blockIdx.x < 64) for (int it = ((int)blockIdx.x - 32) * NWAVES + wave; it < I_BA + I_BB + I_O + I_UP + I_DN; it += 32 * NWAVES) {
;                     int r = it;
;                     if (r < I_BA) { const int kb = r / 32, nb = r % 32; p0_transpose_item(wba, 1024, 32 * nb, 64 * kb, WBAB_T, 1024, 32 * nb, 0, scr, lane); continue; } r -= I_BA;
;                     if (r < I_BB) { const int kb = r / 32, nb = r % 32; p0_transpose_item(wbb, 1024, 32 * nb, 64 * kb, WBAB_T, 1024, 32 * nb, 512, scr, lane); continue; } r -= I_BB;
.LBB0_833:
	s_andn2_b64 vcc, exec, s[6:7]
	s_cbranch_vccnz .LBB0_835
	s_and_b32 s0, s8, 0x3c0
	s_add_i32 s6, s0, 0xfffffe00
	v_or_b32_e32 v2, s6, v1
	v_lshlrev_b64 v[48:49], 12, v[2:3]
	v_or_b32_e32 v2, s6, v24
	v_lshlrev_b64 v[50:51], 12, v[2:3]
	v_or_b32_e32 v2, s6, v25
	v_lshlrev_b64 v[56:57], 12, v[2:3]
	v_or_b32_e32 v2, s6, v26
	s_and_b32 s3, s5, 0x3e0
	v_lshlrev_b64 v[58:59], 12, v[2:3]
	v_or_b32_e32 v2, s6, v27
	s_lshl_b32 s0, s3, 2
	v_lshlrev_b64 v[64:65], 12, v[2:3]
	v_or_b32_e32 v2, s6, v28
	v_lshl_add_u64 v[76:77], v[16:17], 0, s[0:1]
	v_lshlrev_b64 v[66:67], 12, v[2:3]
	v_lshl_add_u64 v[48:49], v[76:77], 0, v[48:49]
	v_lshl_add_u64 v[52:53], v[76:77], 0, v[50:51]
	v_lshl_add_u64 v[56:57], v[76:77], 0, v[56:57]
	v_lshl_add_u64 v[60:61], v[76:77], 0, v[58:59]
	v_lshl_add_u64 v[64:65], v[76:77], 0, v[64:65]
	v_lshl_add_u64 v[68:69], v[76:77], 0, v[66:67]
	global_load_dwordx4 v[48:51], v[48:49], off nt
	s_nop 0
	global_load_dwordx4 v[52:55], v[52:53], off nt
	s_nop 0
	global_load_dwordx4 v[56:59], v[56:57], off nt
	s_nop 0
	global_load_dwordx4 v[60:63], v[60:61], off nt
	s_nop 0
	global_load_dwordx4 v[64:67], v[64:65], off nt
	s_nop 0
	global_load_dwordx4 v[68:71], v[68:69], off nt
	v_or_b32_e32 v2, s6, v29
	v_lshlrev_b64 v[72:73], 12, v[2:3]
	v_lshl_add_u64 v[72:73], v[76:77], 0, v[72:73]
	v_or_b32_e32 v2, s6, v30
	global_load_dwordx4 v[72:75], v[72:73], off nt
	v_lshlrev_b64 v[78:79], 12, v[2:3]
	v_lshl_add_u64 v[76:77], v[76:77], 0, v[78:79]
	global_load_dwordx4 v[76:79], v[76:77], off nt
	s_mov_b32 s7, s1
	v_or_b32_e32 v2, s3, v1
	v_or_b32_e32 v47, s3, v24
	v_lshl_add_u64 v[80:81], s[6:7], 1, v[18:19]
	v_lshlrev_b32_e32 v2, 11, v2
	v_or_b32_e32 v86, s3, v25
	v_lshl_add_u64 v[82:83], v[80:81], 0, v[2:3]
	v_lshlrev_b32_e32 v2, 11, v47
	v_or_b32_e32 v92, s3, v26
	v_lshl_add_u64 v[84:85], v[80:81], 0, v[2:3]
	v_lshlrev_b32_e32 v2, 11, v86
	v_lshl_add_u64 v[86:87], v[80:81], 0, v[2:3]
	v_lshlrev_b32_e32 v2, 11, v92
	s_waitcnt vmcnt(7)
	ds_write2_b32 v32, v48, v49 offset1:1
	ds_write2_b32 v32, v50, v51 offset0:2 offset1:3
	s_waitcnt vmcnt(6)
	ds_write2_b32 v33, v52, v53 offset1:1
	ds_write2_b32 v34, v54, v55 offset1:1
	s_waitcnt vmcnt(5)
	ds_write2_b32 v35, v56, v57 offset1:1
	ds_write2_b32 v36, v58, v59 offset1:1
	s_waitcnt vmcnt(4)
	ds_write2_b32 v37, v60, v61 offset1:1
	ds_write2_b32 v38, v62, v63 offset1:1
	s_waitcnt vmcnt(3)
	ds_write2_b32 v39, v64, v65 offset1:1
	ds_write2_b32 v40, v66, v67 offset1:1
	s_waitcnt vmcnt(2)
	ds_write2_b32 v41, v68, v69 offset1:1
	ds_write2_b32 v42, v70, v71 offset1:1
	s_waitcnt vmcnt(1)
	ds_write2_b32 v43, v72, v73 offset1:1
	ds_write2_b32 v44, v74, v75 offset1:1
	s_waitcnt vmcnt(0)
	ds_write2_b32 v45, v76, v77 offset1:1
	ds_write2_b32 v46, v78, v79 offset1:1
	s_waitcnt lgkmcnt(0)
	ds_read2_b32 v[52:53], v31 offset0:33 offset1:41
	ds_read2_b32 v[54:55], v31 offset1:8
	ds_read2_b32 v[56:57], v31 offset0:66 offset1:74
	ds_read2_b32 v[58:59], v31 offset0:99 offset1:107
	ds_read2_b32 v[60:61], v31 offset0:132 offset1:140
	ds_read2_b32 v[62:63], v31 offset0:165 offset1:173
	ds_read2_b32 v[64:65], v31 offset0:198 offset1:206
	ds_read2_b32 v[66:67], v31 offset0:231 offset1:239
	ds_read2_b32 v[68:69], v31 offset0:49 offset1:57
	ds_read2_b32 v[70:71], v31 offset0:16 offset1:24
	ds_read2_b32 v[72:73], v31 offset0:82 offset1:90
	ds_read2_b32 v[74:75], v31 offset0:115 offset1:123
	ds_read2_b32 v[76:77], v31 offset0:148 offset1:156
	ds_read2_b32 v[78:79], v31 offset0:181 offset1:189
	ds_read2_b32 v[88:89], v31 offset0:214 offset1:222
	ds_read2_b32 v[90:91], v31 offset0:247 offset1:255
	s_waitcnt lgkmcnt(14)
	v_cvt_pk_bf16_f32 v48, v54, v52
	s_waitcnt lgkmcnt(12)
	v_cvt_pk_bf16_f32 v49, v56, v58
	s_waitcnt lgkmcnt(10)
	v_cvt_pk_bf16_f32 v50, v60, v62
	s_waitcnt lgkmcnt(8)
	v_cvt_pk_bf16_f32 v51, v64, v66
	v_cvt_pk_bf16_f32 v52, v55, v53
	v_cvt_pk_bf16_f32 v53, v57, v59
	v_cvt_pk_bf16_f32 v54, v61, v63
	v_cvt_pk_bf16_f32 v55, v65, v67
	s_waitcnt lgkmcnt(6)
	v_cvt_pk_bf16_f32 v56, v70, v68
	s_waitcnt lgkmcnt(4)
	v_cvt_pk_bf16_f32 v57, v72, v74
	s_waitcnt lgkmcnt(2)
	v_cvt_pk_bf16_f32 v58, v76, v78
	s_waitcnt lgkmcnt(0)
	v_cvt_pk_bf16_f32 v59, v88, v90
	v_cvt_pk_bf16_f32 v60, v71, v69
	v_cvt_pk_bf16_f32 v61, v73, v75
	v_cvt_pk_bf16_f32 v62, v77, v79
	v_cvt_pk_bf16_f32 v63, v89, v91
	global_store_dwordx4 v[82:83], v[48:51], off
	global_store_dwordx4 v[84:85], v[52:55], off
	global_store_dwordx4 v[86:87], v[56:59], off
	v_lshl_add_u64 v[48:49], v[80:81], 0, v[2:3]
	global_store_dwordx4 v[48:49], v[60:63], off
	s_waitcnt lgkmcnt(0)

; #define GAS __attribute__((address_space(1)))
; #define LAS __attribute__((address_space(3)))
; #define LDS_WAIT() asm volatile("s_waitcnt lgkmcnt(0)" ::: "memory")
; __device__ __forceinline__ unsigned pk2(float lo, float hi) { const f32x2_t v = {lo, hi}; return __builtin_bit_cast(unsigned, __builtin_convertvector(v, bf16x2_t)); }
; __device__ __forceinline__ void p0_transpose_item(const float* W, int ldw, int src_col0, int k0, bf16_t* WT, int ldk, int dst_row0, int dst_k0, LAS float* scr, int lane) {
; #pragma unroll
;     for (int i = 0; i < 8; ++i) { const int kk = 8 * i + (lane >> 3), n4 = 4 * (lane & 7);
;         const f32x4 w = *(const GAS f32x4*)(W + (size_t)(k0 + kk) * ldw + src_col0 + n4); LAS float* d = scr + kk * 33 + n4; d[0] = w[0]; d[1] = w[1]; d[2] = w[2]; d[3] = w[3]; }
;     LDS_WAIT(); asm volatile("" ::: "memory");
;     const int c = lane & 7;
; #pragma unroll
;     for (int j = 0; j < 4; ++j) { const int n = (lane >> 3) + 8 * j; const LAS float* s = scr + (8 * c) * 33 + n;
;         v4u o; o.x = pk2(s[0 * 33], s[1 * 33]); o.y = pk2(s[2 * 33], s[3 * 33]); o.z = pk2(s[4 * 33], s[5 * 33]); o.w = pk2(s[6 * 33], s[7 * 33]);
;         *(GAS v4u*)(WT + (size_t)(dst_row0 + n) * ldk + dst_k0 + k0 + 8 * c) = o; }
;     LDS_WAIT(); asm volatile("" ::: "memory");
; __global__ void __launch_bounds__(NWAVES * 64, 2) fwd(Args args) {
;     ...
;                 if (blockIdx.x < 64) for (int it = ((int)blockIdx.x - 32) * NWAVES + wave; it < I_BA + I_BB + I_O + I_UP + I_DN; it += 32 * NWAVES) {
;                     int r = it;
;                     if (r < I_BA) { const int kb = r / 32, nb = r % 32; p0_transpose_item(wba, 1024, 32 * nb, 64 * kb, WBAB_T, 1024, 32 * nb, 0, scr, lane); continue; } r -= I_BA;
.LBB0_836:
	s_andn2_b64 vcc, exec, s[6:7]
	s_cbranch_vccnz .LBB0_821
	s_ashr_i32 s0, s4, 31
	s_lshr_b32 s0, s0, 27
	s_add_i32 s0, s4, s0
	s_ashr_i32 s0, s0, 5
	s_lshl_b32 s3, s0, 10
	s_lshl_b32 s10, s0, 6
	s_sub_i32 s6, s5, s3
	v_or_b32_e32 v48, s10, v1
	v_or_b32_e32 v50, s10, v24
	v_or_b32_e32 v56, s10, v25
	v_or_b32_e32 v58, s10, v26
	v_or_b32_e32 v64, s10, v27
	v_or_b32_e32 v66, s10, v28
	s_ashr_i32 s7, s6, 31
	v_ashrrev_i32_e32 v49, 31, v48
	v_ashrrev_i32_e32 v51, 31, v50
	v_ashrrev_i32_e32 v57, 31, v56
	v_ashrrev_i32_e32 v59, 31, v58
	v_ashrrev_i32_e32 v65, 31, v64
	v_ashrrev_i32_e32 v67, 31, v66
	v_lshl_add_u64 v[76:77], s[6:7], 2, v[20:21]
	v_lshlrev_b64 v[48:49], 12, v[48:49]
	v_lshlrev_b64 v[50:51], 12, v[50:51]
	v_lshlrev_b64 v[56:57], 12, v[56:57]
	v_lshlrev_b64 v[58:59], 12, v[58:59]
	v_lshlrev_b64 v[64:65], 12, v[64:65]
	v_lshlrev_b64 v[66:67], 12, v[66:67]
	v_lshl_add_u64 v[48:49], v[76:77], 0, v[48:49]
	v_lshl_add_u64 v[52:53], v[76:77], 0, v[50:51]
	v_lshl_add_u64 v[56:57], v[76:77], 0, v[56:57]
	v_lshl_add_u64 v[60:61], v[76:77], 0, v[58:59]
	v_lshl_add_u64 v[64:65], v[76:77], 0, v[64:65]
	v_lshl_add_u64 v[68:69], v[76:77], 0, v[66:67]
	global_load_dwordx4 v[48:51], v[48:49], off nt
	s_nop 0
	global_load_dwordx4 v[52:55], v[52:53], off nt
	s_nop 0
	global_load_dwordx4 v[56:59], v[56:57], off nt
	s_nop 0
	global_load_dwordx4 v[60:63], v[60:61], off nt
	s_nop 0
	global_load_dwordx4 v[64:67], v[64:65], off nt
	s_nop 0
	global_load_dwordx4 v[68:71], v[68:69], off nt
	v_or_b32_e32 v72, s10, v29
	v_ashrrev_i32_e32 v73, 31, v72
	v_lshlrev_b64 v[72:73], 12, v[72:73]
	v_or_b32_e32 v78, s10, v30
	v_lshl_add_u64 v[72:73], v[76:77], 0, v[72:73]
	v_ashrrev_i32_e32 v79, 31, v78
	global_load_dwordx4 v[72:75], v[72:73], off nt
	v_lshlrev_b64 v[78:79], 12, v[78:79]
	v_lshl_add_u64 v[76:77], v[76:77], 0, v[78:79]
	global_load_dwordx4 v[76:79], v[76:77], off nt
	v_add_u32_e32 v82, s6, v1
	s_ashr_i32 s11, s10, 31
	v_ashrrev_i32_e32 v83, 31, v82
	v_lshl_add_u64 v[80:81], s[10:11], 1, v[22:23]
	v_lshlrev_b64 v[86:87], 11, v[82:83]
	v_add_u32_e32 v84, 8, v82
	v_lshl_add_u64 v[86:87], v[80:81], 0, v[86:87]
	v_ashrrev_i32_e32 v85, 31, v84
	v_lshlrev_b64 v[84:85], 11, v[84:85]
	v_lshl_add_u64 v[84:85], v[80:81], 0, v[84:85]
	s_waitcnt vmcnt(7)
	ds_write2_b32 v32, v48, v49 offset1:1
	ds_write2_b32 v32, v50, v51 offset0:2 offset1:3
	s_waitcnt vmcnt(6)
	ds_write2_b32 v33, v52, v53 offset1:1
	ds_write2_b32 v34, v54, v55 offset1:1
	s_waitcnt vmcnt(5)
	ds_write2_b32 v35, v56, v57 offset1:1
	ds_write2_b32 v36, v58, v59 offset1:1
	s_waitcnt vmcnt(4)
	ds_write2_b32 v37, v60, v61 offset1:1
	ds_write2_b32 v38, v62, v63 offset1:1
	s_waitcnt vmcnt(3)
	ds_write2_b32 v39, v64, v65 offset1:1
	ds_write2_b32 v40, v66, v67 offset1:1
	s_waitcnt vmcnt(2)
	ds_write2_b32 v41, v68, v69 offset1:1
	ds_write2_b32 v42, v70, v71 offset1:1
	s_waitcnt vmcnt(1)
	ds_write2_b32 v43, v72, v73 offset1:1
	ds_write2_b32 v44, v74, v75 offset1:1
	s_waitcnt vmcnt(0)
	ds_write2_b32 v45, v76, v77 offset1:1
	ds_write2_b32 v46, v78, v79 offset1:1
	s_waitcnt lgkmcnt(0)
	ds_read2_b32 v[52:53], v31 offset0:33 offset1:41
	ds_read2_b32 v[54:55], v31 offset1:8
	ds_read2_b32 v[56:57], v31 offset0:66 offset1:74
	ds_read2_b32 v[58:59], v31 offset0:99 offset1:107
	ds_read2_b32 v[60:61], v31 offset0:132 offset1:140
	ds_read2_b32 v[62:63], v31 offset0:165 offset1:173
	ds_read2_b32 v[64:65], v31 offset0:198 offset1:206
	ds_read2_b32 v[66:67], v31 offset0:231 offset1:239
	ds_read2_b32 v[68:69], v31 offset0:49 offset1:57
	ds_read2_b32 v[70:71], v31 offset0:16 offset1:24
	ds_read2_b32 v[72:73], v31 offset0:82 offset1:90
	ds_read2_b32 v[74:75], v31 offset0:115 offset1:123
	ds_read2_b32 v[76:77], v31 offset0:148 offset1:156
	s_waitcnt lgkmcnt(11)
	v_cvt_pk_bf16_f32 v48, v54, v52
	s_waitcnt lgkmcnt(9)
	v_cvt_pk_bf16_f32 v49, v56, v58
	s_waitcnt lgkmcnt(7)
	v_cvt_pk_bf16_f32 v50, v60, v62
	s_waitcnt lgkmcnt(5)
	v_cvt_pk_bf16_f32 v51, v64, v66
	global_store_dwordx4 v[86:87], v[48:51], off
	v_cvt_pk_bf16_f32 v52, v55, v53
	v_cvt_pk_bf16_f32 v53, v57, v59
	v_cvt_pk_bf16_f32 v54, v61, v63
	ds_read2_b32 v[56:57], v31 offset0:181 offset1:189
	ds_read2_b32 v[58:59], v31 offset0:214 offset1:222
	ds_read2_b32 v[60:61], v31 offset0:247 offset1:255
	v_cvt_pk_bf16_f32 v55, v65, v67
	global_store_dwordx4 v[84:85], v[52:55], off
	s_waitcnt lgkmcnt(6)
	v_cvt_pk_bf16_f32 v48, v70, v68
	s_waitcnt lgkmcnt(4)
	v_cvt_pk_bf16_f32 v49, v72, v74
	v_add_u32_e32 v52, 16, v82
	v_ashrrev_i32_e32 v53, 31, v52
	v_lshlrev_b64 v[52:53], 11, v[52:53]
	s_waitcnt lgkmcnt(2)
	v_cvt_pk_bf16_f32 v50, v76, v56
	s_waitcnt lgkmcnt(0)
	v_cvt_pk_bf16_f32 v51, v58, v60
	v_lshl_add_u64 v[52:53], v[80:81], 0, v[52:53]
	global_store_dwordx4 v[52:53], v[48:51], off
	v_add_u32_e32 v52, 24, v82
	v_ashrrev_i32_e32 v53, 31, v52
	v_lshlrev_b64 v[52:53], 11, v[52:53]
	v_cvt_pk_bf16_f32 v48, v71, v69
	v_cvt_pk_bf16_f32 v49, v73, v75
	v_cvt_pk_bf16_f32 v50, v77, v57
	v_cvt_pk_bf16_f32 v51, v59, v61
	v_lshl_add_u64 v[52:53], v[80:81], 0, v[52:53]
	global_store_dwordx4 v[52:53], v[48:51], off
	s_waitcnt lgkmcnt(0)
	s_branch .LBB0_821
